# GLA pass B re-reads the cumulative gate decays pass A already computed (kept in the idle ACT buffer) instead of recomputing them
# speedup vs baseline: 1.0213x; 1.0213x over previous
.LBB0_602:
	s_add_i32 s98, s76, s10
	s_lshl_b32 s98, s98, 1
	s_lshl_b32 s99, s10, 1
	s_add_i32 s99, s6, s99
	s_and_b64 s[100:101], s[24:25], exec
	s_cselect_b32 s98, s98, s99
	s_or_b32 s98, s98, s14
	s_lshl_b32 s98, s98, 14
	s_load_dwordx2 s[100:101], s[8:9], 0x140
	v_lshlrev_b32_e32 v196, 5, v202
	s_waitcnt lgkmcnt(0)
	s_add_u32 s100, s100, 0x4f28000
	s_addc_u32 s101, s101, 0
	s_add_u32 s100, s100, s98
	s_addc_u32 s101, s101, 0
	global_load_dwordx4 v[228:231], v196, s[100:101]
	global_load_dwordx4 v[232:235], v196, s[100:101] offset:16
	v_cndmask_b32_e64 v0, v94, v85, s[74:75]
	v_add_u32_e32 v0, s18, v0
	v_mad_i64_i32 v[2:3], s[20:21], v0, s88, v[22:23]
	v_cndmask_b32_e64 v0, v95, v84, s[74:75]
	v_add_u32_e32 v0, s18, v0
	global_load_ushort v157, v[2:3], off
	global_load_ushort v156, v[2:3], off offset:512
	v_mad_i64_i32 v[2:3], s[20:21], v0, s88, v[22:23]
	v_cndmask_b32_e64 v0, v96, v82, s[74:75]
	v_add_u32_e32 v0, s18, v0
	global_load_ushort v155, v[2:3], off
	global_load_ushort v154, v[2:3], off offset:512
	v_mad_i64_i32 v[2:3], s[20:21], v0, s88, v[22:23]
	v_cndmask_b32_e64 v0, v97, v81, s[74:75]
	v_add_u32_e32 v0, s18, v0
	global_load_ushort v153, v[2:3], off
	global_load_ushort v152, v[2:3], off offset:512
	v_mad_i64_i32 v[2:3], s[20:21], v0, s88, v[22:23]
	v_cndmask_b32_e64 v0, v98, v77, s[74:75]
	v_add_u32_e32 v0, s18, v0
	global_load_ushort v151, v[2:3], off
	global_load_ushort v150, v[2:3], off offset:512
	v_mad_i64_i32 v[2:3], s[20:21], v0, s88, v[22:23]
	v_cndmask_b32_e64 v0, v99, v75, s[74:75]
	v_add_u32_e32 v0, s18, v0
	global_load_ushort v149, v[2:3], off
	global_load_ushort v148, v[2:3], off offset:512
	v_mad_i64_i32 v[2:3], s[20:21], v0, s88, v[22:23]
	v_cndmask_b32_e64 v0, v100, v66, s[74:75]
	v_add_u32_e32 v0, s18, v0
	global_load_ushort v147, v[2:3], off
	global_load_ushort v146, v[2:3], off offset:512
	v_mad_i64_i32 v[2:3], s[20:21], v0, s88, v[22:23]
	v_cndmask_b32_e64 v0, v101, v65, s[74:75]
	v_add_u32_e32 v0, s18, v0
	global_load_ushort v145, v[2:3], off
	global_load_ushort v144, v[2:3], off offset:512
	v_mad_i64_i32 v[2:3], s[20:21], v0, s88, v[22:23]
	v_mov_b32_e32 v0, v202
	global_load_ushort v143, v[2:3], off
	global_load_ushort v142, v[2:3], off offset:512
	s_andn2_b64 vcc, exec, s[86:87]
	v_ashrrev_i32_e32 v6, 3, v0
	v_and_b32_e32 v11, -16, v6
	v_and_b32_e32 v10, 0x7f, v0
	v_sub_u32_e32 v0, 63, v11
	v_sub_u32_e32 v2, 62, v11
	v_or_b32_e32 v3, 1, v11
	v_cndmask_b32_e64 v0, v0, v11, s[74:75]
	v_cndmask_b32_e64 v2, v2, v3, s[74:75]
	v_add_u32_e32 v0, s18, v0
	v_add_u32_e32 v7, s18, v2
	v_mov_b64_e32 v[2:3], s[94:95]
	v_mad_i64_i32 v[4:5], s[20:21], v0, s88, v[2:3]
	v_lshlrev_b32_e32 v0, 1, v10
	v_lshl_add_u64 v[4:5], v[4:5], 0, v[0:1]
	global_load_ushort v8, v[4:5], off offset:1024
	v_mad_i64_i32 v[4:5], s[20:21], v7, s88, v[2:3]
	v_lshl_add_u64 v[4:5], v[4:5], 0, v[0:1]
	global_load_ushort v7, v[4:5], off offset:1024
	v_or_b32_e32 v4, 2, v11
	v_sub_u32_e32 v5, 63, v4
	v_cndmask_b32_e64 v5, v5, v4, s[74:75]
	v_sub_u32_e32 v4, 62, v4
	v_or_b32_e32 v9, 3, v11
	v_add_u32_e32 v5, s18, v5
	v_cndmask_b32_e64 v4, v4, v9, s[74:75]
	v_add_u32_e32 v9, s18, v4
	v_mad_i64_i32 v[4:5], s[20:21], v5, s88, v[2:3]
	v_lshl_add_u64 v[4:5], v[4:5], 0, v[0:1]
	global_load_ushort v12, v[4:5], off offset:1024
	v_mad_i64_i32 v[4:5], s[20:21], v9, s88, v[2:3]
	v_lshl_add_u64 v[4:5], v[4:5], 0, v[0:1]
	global_load_ushort v9, v[4:5], off offset:1024
	v_or_b32_e32 v4, 4, v11
	v_sub_u32_e32 v5, 63, v4
	v_cndmask_b32_e64 v5, v5, v4, s[74:75]
	v_sub_u32_e32 v4, 62, v4
	v_or_b32_e32 v13, 5, v11
	v_add_u32_e32 v5, s18, v5
	v_cndmask_b32_e64 v4, v4, v13, s[74:75]
	v_add_u32_e32 v13, s18, v4
	v_mad_i64_i32 v[4:5], s[20:21], v5, s88, v[2:3]
	v_lshl_add_u64 v[4:5], v[4:5], 0, v[0:1]
	global_load_ushort v14, v[4:5], off offset:1024
	v_mad_i64_i32 v[4:5], s[20:21], v13, s88, v[2:3]
	v_lshl_add_u64 v[4:5], v[4:5], 0, v[0:1]
	global_load_ushort v13, v[4:5], off offset:1024
	v_or_b32_e32 v4, 6, v11
	v_sub_u32_e32 v5, 63, v4
	v_cndmask_b32_e64 v5, v5, v4, s[74:75]
	v_sub_u32_e32 v4, 62, v4
	v_or_b32_e32 v15, 7, v11
	v_add_u32_e32 v5, s18, v5
	v_cndmask_b32_e64 v4, v4, v15, s[74:75]
	v_add_u32_e32 v15, s18, v4
	v_mad_i64_i32 v[4:5], s[20:21], v5, s88, v[2:3]
	v_lshl_add_u64 v[4:5], v[4:5], 0, v[0:1]
	global_load_ushort v16, v[4:5], off offset:1024
	v_mad_i64_i32 v[4:5], s[20:21], v15, s88, v[2:3]
	v_lshl_add_u64 v[4:5], v[4:5], 0, v[0:1]
	global_load_ushort v15, v[4:5], off offset:1024
	v_or_b32_e32 v4, 8, v11
	v_sub_u32_e32 v5, 63, v4
	v_cndmask_b32_e64 v5, v5, v4, s[74:75]
	v_sub_u32_e32 v4, 62, v4
	v_or_b32_e32 v17, 9, v11
	v_add_u32_e32 v5, s18, v5
	v_cndmask_b32_e64 v4, v4, v17, s[74:75]
	v_add_u32_e32 v17, s18, v4
	v_mad_i64_i32 v[4:5], s[20:21], v5, s88, v[2:3]
	v_lshl_add_u64 v[4:5], v[4:5], 0, v[0:1]
	global_load_ushort v60, v[4:5], off offset:1024
	v_mad_i64_i32 v[4:5], s[20:21], v17, s88, v[2:3]
	v_lshl_add_u64 v[4:5], v[4:5], 0, v[0:1]
	global_load_ushort v17, v[4:5], off offset:1024
	v_or_b32_e32 v4, 10, v11
	v_sub_u32_e32 v5, 63, v4
	v_cndmask_b32_e64 v5, v5, v4, s[74:75]
	v_sub_u32_e32 v4, 62, v4
	v_or_b32_e32 v61, 11, v11
	v_add_u32_e32 v5, s18, v5
	v_cndmask_b32_e64 v4, v4, v61, s[74:75]
	v_add_u32_e32 v61, s18, v4
	v_mad_i64_i32 v[4:5], s[20:21], v5, s88, v[2:3]
	v_lshl_add_u64 v[4:5], v[4:5], 0, v[0:1]
	global_load_ushort v158, v[4:5], off offset:1024
	v_mad_i64_i32 v[4:5], s[20:21], v61, s88, v[2:3]
	v_lshl_add_u64 v[4:5], v[4:5], 0, v[0:1]
	global_load_ushort v61, v[4:5], off offset:1024
	v_or_b32_e32 v4, 12, v11
	v_sub_u32_e32 v5, 63, v4
	v_cndmask_b32_e64 v5, v5, v4, s[74:75]
	v_sub_u32_e32 v4, 62, v4
	v_or_b32_e32 v159, 13, v11
	v_add_u32_e32 v5, s18, v5
	v_cndmask_b32_e64 v4, v4, v159, s[74:75]
	v_add_u32_e32 v159, s18, v4
	v_mad_i64_i32 v[4:5], s[20:21], v5, s88, v[2:3]
	v_lshl_add_u64 v[4:5], v[4:5], 0, v[0:1]
	global_load_ushort v160, v[4:5], off offset:1024
	v_mad_i64_i32 v[4:5], s[20:21], v159, s88, v[2:3]
	v_lshl_add_u64 v[4:5], v[4:5], 0, v[0:1]
	global_load_ushort v159, v[4:5], off offset:1024
	v_or_b32_e32 v4, 14, v11
	v_sub_u32_e32 v5, 63, v4
	v_cndmask_b32_e64 v5, v5, v4, s[74:75]
	v_sub_u32_e32 v4, 62, v4
	v_or_b32_e32 v6, 15, v6
	v_cndmask_b32_e64 v4, v4, v6, s[74:75]
	v_add_u32_e32 v5, s18, v5
	v_add_u32_e32 v6, s18, v4
	v_mad_i64_i32 v[4:5], s[20:21], v5, s88, v[2:3]
	v_mad_i64_i32 v[2:3], s[20:21], v6, s88, v[2:3]
	v_lshl_add_u64 v[4:5], v[4:5], 0, v[0:1]
	v_lshl_add_u64 v[2:3], v[2:3], 0, v[0:1]
	global_load_ushort v161, v[4:5], off offset:1024
	global_load_ushort v0, v[2:3], off offset:1024
	s_waitcnt vmcnt(12)
	v_lshl_or_b32 v3, v9, 16, v12
	v_lshl_or_b32 v2, v7, 16, v8
	s_waitcnt vmcnt(10)
	v_lshl_or_b32 v4, v13, 16, v14
	s_waitcnt vmcnt(8)
	v_lshl_or_b32 v5, v15, 16, v16
	s_waitcnt vmcnt(6)
	v_lshl_or_b32 v6, v17, 16, v60
	s_waitcnt vmcnt(4)
	v_lshl_or_b32 v7, v61, 16, v158
	s_waitcnt vmcnt(2)
	v_lshl_or_b32 v8, v159, 16, v160
	s_waitcnt vmcnt(0)
	v_lshl_or_b32 v9, v0, 16, v161
	v_mul_u32_u24_e32 v0, 0x90, v10
	v_lshlrev_b32_e32 v10, 1, v11
	v_add3_u32 v0, 0, v0, v10
	ds_write_b128 v0, v[2:5] offset:61440
	ds_write_b128 v0, v[6:9] offset:61456
	s_cbranch_vccnz .LBB0_604
	s_and_b64 s[20:21], s[74:75], exec
	s_cselect_b32 s4, 16, 24
	s_add_u32 s20, s8, s4
	s_addc_u32 s21, s9, 0
	s_load_dwordx2 s[20:21], s[20:21], 0x0
	s_waitcnt lgkmcnt(0)
	s_add_u32 s4, s20, s82
	s_addc_u32 s5, s21, s83
	s_add_u32 s20, s4, s91
	s_addc_u32 s21, s5, 0
	v_lshl_add_u64 v[10:11], v[24:25], 2, s[20:21]
	v_add_co_u32_e32 v60, vcc, 0x1000, v10
	global_load_dword v2, v[10:11], off
	global_load_dword v3, v[10:11], off offset:512
	global_load_dword v4, v[10:11], off offset:1024
	global_load_dword v5, v[10:11], off offset:1536
	global_load_dword v6, v[10:11], off offset:2048
	global_load_dword v7, v[10:11], off offset:2560
	global_load_dword v8, v[10:11], off offset:3072
	global_load_dword v9, v[10:11], off offset:3584
	v_addc_co_u32_e32 v61, vcc, 0, v11, vcc
	global_load_dword v10, v[60:61], off
	global_load_dword v11, v[60:61], off offset:512
	global_load_dword v12, v[60:61], off offset:1024
	global_load_dword v13, v[60:61], off offset:1536
	global_load_dword v14, v[60:61], off offset:2048
	global_load_dword v15, v[60:61], off offset:2560
	global_load_dword v16, v[60:61], off offset:3072
	global_load_dword v17, v[60:61], off offset:3584
	s_and_b64 s[20:21], s[74:75], exec
	s_cselect_b32 s15, s10, s11
	s_cmp_lt_i32 s15, 1
	s_cbranch_scc0 .LBB0_605
	s_branch .LBB0_610

.LBB0_613:
	v_mov_b32_e32 v160, v228
	v_mov_b32_e32 v161, v229
	v_mov_b32_e32 v162, v230
	v_mov_b32_e32 v163, v231
	v_mov_b32_e32 v164, v232
	v_mov_b32_e32 v165, v233
	v_mov_b32_e32 v166, v234
	v_mov_b32_e32 v6, v235
	v_mov_b32_e32 v0, 0
	v_add_f32_e32 v2, v160, v0
	v_mul_f32_e32 v10, 0x3fb8aa3b, v2
	v_exp_f32_e32 v10, v10
	v_mul_f32_e32 v2, 0xbfb8aa3b, v2
	v_exp_f32_e32 v2, v2
	v_add_f32_e32 v3, v161, v0
	v_add_f32_e32 v4, v162, v0
	v_add_f32_e32 v5, v163, v0
	v_add_f32_e32 v7, v0, v164
	v_add_f32_e32 v8, v0, v165
	v_add_f32_e32 v9, v0, v166
	v_add_f32_e32 v0, v0, v6
	v_lshlrev_b32_e32 v6, 16, v157
	v_mul_f32_e32 v6, 0x3e000000, v6
	v_mul_f32_e32 v6, v6, v10
	v_lshlrev_b32_e32 v10, 16, v156
	v_mul_f32_e32 v2, v2, v10
	v_bfe_u32 v10, v6, 16, 1
	v_add3_u32 v6, v6, v10, s27
	ds_write_b16_d16_hi v102, v6 offset:33792
	v_bfe_u32 v6, v2, 16, 1
	v_add3_u32 v2, v2, v6, s27
	v_mul_f32_e32 v6, 0x3fb8aa3b, v3
	v_exp_f32_e32 v6, v6
	v_mul_f32_e32 v3, 0xbfb8aa3b, v3
	v_exp_f32_e32 v3, v3
	ds_write_b16_d16_hi v102, v2 offset:43008
	v_lshlrev_b32_e32 v2, 16, v155
	v_mul_f32_e32 v2, 0x3e000000, v2
	v_mul_f32_e32 v2, v2, v6
	v_lshlrev_b32_e32 v6, 16, v154
	v_mul_f32_e32 v3, v3, v6
	v_bfe_u32 v6, v2, 16, 1
	v_add3_u32 v2, v2, v6, s27
	ds_write_b16_d16_hi v103, v2 offset:33792
	v_bfe_u32 v2, v3, 16, 1
	v_add3_u32 v2, v3, v2, s27
	v_mul_f32_e32 v3, 0x3fb8aa3b, v4
	v_exp_f32_e32 v3, v3
	v_mul_f32_e32 v4, 0xbfb8aa3b, v4
	v_exp_f32_e32 v4, v4
	ds_write_b16_d16_hi v103, v2 offset:43008
	v_lshlrev_b32_e32 v2, 16, v153
	v_mul_f32_e32 v2, 0x3e000000, v2
	v_mul_f32_e32 v2, v2, v3
	v_lshlrev_b32_e32 v3, 16, v152
	v_mul_f32_e32 v3, v4, v3
	v_bfe_u32 v4, v2, 16, 1
	v_add3_u32 v2, v2, v4, s27
	ds_write_b16_d16_hi v104, v2 offset:33792
	v_bfe_u32 v2, v3, 16, 1
	v_add3_u32 v2, v3, v2, s27
	v_mul_f32_e32 v3, 0x3fb8aa3b, v5
	v_exp_f32_e32 v3, v3
	v_mul_f32_e32 v4, 0xbfb8aa3b, v5
	v_exp_f32_e32 v4, v4
	ds_write_b16_d16_hi v104, v2 offset:43008
	v_lshlrev_b32_e32 v2, 16, v151
	v_mul_f32_e32 v2, 0x3e000000, v2
	v_mul_f32_e32 v2, v2, v3
	v_lshlrev_b32_e32 v3, 16, v150
	v_mul_f32_e32 v3, v4, v3
	v_bfe_u32 v4, v2, 16, 1
	v_add3_u32 v2, v2, v4, s27
	ds_write_b16_d16_hi v105, v2 offset:33792
	v_bfe_u32 v2, v3, 16, 1
	v_add3_u32 v2, v3, v2, s27
	v_mul_f32_e32 v3, 0x3fb8aa3b, v7
	v_exp_f32_e32 v3, v3
	v_mul_f32_e32 v4, 0xbfb8aa3b, v7
	v_exp_f32_e32 v4, v4
	ds_write_b16_d16_hi v105, v2 offset:43008
	v_lshlrev_b32_e32 v2, 16, v149
	v_mul_f32_e32 v2, 0x3e000000, v2
	v_mul_f32_e32 v2, v2, v3
	v_lshlrev_b32_e32 v3, 16, v148
	v_mul_f32_e32 v3, v4, v3
	v_bfe_u32 v4, v2, 16, 1
	v_add3_u32 v2, v2, v4, s27
	ds_write_b16_d16_hi v106, v2 offset:33792
	v_bfe_u32 v2, v3, 16, 1
	v_add3_u32 v2, v3, v2, s27
	v_mul_f32_e32 v3, 0x3fb8aa3b, v8
	v_exp_f32_e32 v3, v3
	v_mul_f32_e32 v4, 0xbfb8aa3b, v8
	v_exp_f32_e32 v4, v4
	ds_write_b16_d16_hi v106, v2 offset:43008
	v_lshlrev_b32_e32 v2, 16, v147
	v_mul_f32_e32 v2, 0x3e000000, v2
	v_mul_f32_e32 v2, v2, v3
	v_lshlrev_b32_e32 v3, 16, v146
	v_mul_f32_e32 v3, v4, v3
	v_bfe_u32 v4, v2, 16, 1
	v_add3_u32 v2, v2, v4, s27
	ds_write_b16_d16_hi v107, v2 offset:33792
	v_bfe_u32 v2, v3, 16, 1
	v_add3_u32 v2, v3, v2, s27
	v_mul_f32_e32 v3, 0x3fb8aa3b, v9
	v_exp_f32_e32 v3, v3
	v_mul_f32_e32 v4, 0xbfb8aa3b, v9
	v_exp_f32_e32 v4, v4
	ds_write_b16_d16_hi v107, v2 offset:43008
	v_lshlrev_b32_e32 v2, 16, v145
	v_mul_f32_e32 v2, 0x3e000000, v2
	v_mul_f32_e32 v2, v2, v3
	v_lshlrev_b32_e32 v3, 16, v144
	v_mul_f32_e32 v3, v4, v3
	v_bfe_u32 v4, v2, 16, 1
	v_add3_u32 v2, v2, v4, s27
	ds_write_b16_d16_hi v108, v2 offset:33792
	v_bfe_u32 v2, v3, 16, 1
	v_add3_u32 v2, v3, v2, s27
	v_mul_f32_e32 v3, 0x3fb8aa3b, v0
	v_exp_f32_e32 v3, v3
	v_mul_f32_e32 v0, 0xbfb8aa3b, v0
	v_exp_f32_e32 v0, v0
	ds_write_b16_d16_hi v108, v2 offset:43008
	v_lshlrev_b32_e32 v2, 16, v143
	v_mul_f32_e32 v2, 0x3e000000, v2
	v_mul_f32_e32 v2, v2, v3
	v_lshlrev_b32_e32 v3, 16, v142
	v_mul_f32_e32 v0, v0, v3
	v_bfe_u32 v3, v2, 16, 1
	v_add3_u32 v2, v2, v3, s27
	ds_write_b16_d16_hi v109, v2 offset:33792
	v_bfe_u32 v2, v0, 16, 1
	v_add3_u32 v0, v0, v2, s27
	ds_write_b16_d16_hi v109, v0 offset:43008
	s_waitcnt lgkmcnt(0)
	s_barrier
	s_and_saveexec_b64 s[92:93], s[40:41]
	s_cbranch_execz .LBB0_623
	v_mov_b32_e32 v0, v202
	s_nop 0
	v_and_b32_e32 v2, 31, v0
	v_mul_u32_u24_e32 v2, 0x48, v2
	v_lshrrev_b32_e32 v0, 1, v0
	v_lshlrev_b32_e32 v6, 1, v2
	v_and_b32_e32 v0, 16, v0
	v_add3_u32 v60, v87, v6, v0
	ds_read_b128 v[2:5], v60 offset:33792
	v_add3_u32 v0, v88, v6, v0
	ds_read_b128 v[6:9], v0 offset:43008
	ds_read_b128 v[142:145], v60 offset:33824
	ds_read_b128 v[146:149], v0 offset:43040
	s_waitcnt lgkmcnt(2)
	v_mfma_f32_32x32x16_bf16 v[2:17], v[2:5], v[6:9], 0
	s_waitcnt lgkmcnt(0)
	v_mfma_f32_32x32x16_bf16 v[2:17], v[142:145], v[146:149], v[2:17]
	ds_read_b128 v[142:145], v60 offset:33856
	ds_read_b128 v[146:149], v0 offset:43072
	s_waitcnt lgkmcnt(0)
	v_mfma_f32_32x32x16_bf16 v[2:17], v[142:145], v[146:149], v[2:17]
	ds_read_b128 v[142:145], v60 offset:33888
	ds_read_b128 v[146:149], v0 offset:43104
	s_waitcnt lgkmcnt(0)
	v_mfma_f32_32x32x16_bf16 v[2:17], v[142:145], v[146:149], v[2:17]
	s_nop 11
	v_cndmask_b32_e64 v0, v2, 0, s[42:43]
	v_cndmask_b32_e64 v2, v3, 0, s[44:45]
	v_cndmask_b32_e64 v3, v4, 0, s[46:47]
	v_cndmask_b32_e64 v4, v5, 0, s[48:49]
	v_cndmask_b32_e64 v5, v6, 0, s[50:51]
	v_cndmask_b32_e64 v6, v7, 0, s[52:53]
	v_cndmask_b32_e64 v7, v8, 0, s[54:55]
	v_cndmask_b32_e64 v8, v9, 0, s[56:57]
	v_bfe_u32 v9, v0, 16, 1
	v_bfe_u32 v60, v2, 16, 1
	v_bfe_u32 v61, v3, 16, 1
	v_bfe_u32 v142, v4, 16, 1
	v_bfe_u32 v143, v5, 16, 1
	v_bfe_u32 v144, v6, 16, 1
	v_bfe_u32 v145, v7, 16, 1
	v_bfe_u32 v146, v8, 16, 1
	v_add3_u32 v0, v0, v9, s27
	v_add3_u32 v2, v2, v60, s27
	v_add3_u32 v3, v3, v61, s27
	v_add3_u32 v4, v4, v142, s27
	v_add3_u32 v5, v5, v143, s27
	v_add3_u32 v6, v6, v144, s27
	v_add3_u32 v7, v7, v145, s27
	ds_write_b16_d16_hi v141, v0 offset:52224
	ds_write_b16_d16_hi v141, v2 offset:52368
	ds_write_b16_d16_hi v141, v3 offset:52512
	ds_write_b16_d16_hi v141, v4 offset:52656
	ds_write_b16_d16_hi v141, v5 offset:53376
	ds_write_b16_d16_hi v141, v6 offset:53520
	ds_write_b16_d16_hi v141, v7 offset:53664
	v_add3_u32 v0, v8, v146, s27
	ds_write_b16_d16_hi v141, v0 offset:53808
	v_cndmask_b32_e64 v0, v10, 0, s[58:59]
	v_bfe_u32 v2, v0, 16, 1
	v_add3_u32 v0, v0, v2, s27
	ds_write_b16_d16_hi v141, v0 offset:54528
	v_cndmask_b32_e64 v0, v11, 0, s[60:61]
	v_bfe_u32 v2, v0, 16, 1
	v_add3_u32 v0, v0, v2, s27
	ds_write_b16_d16_hi v141, v0 offset:54672
	v_cndmask_b32_e64 v0, v12, 0, s[62:63]
	v_bfe_u32 v2, v0, 16, 1
	v_add3_u32 v0, v0, v2, s27
	ds_write_b16_d16_hi v141, v0 offset:54816
	v_cndmask_b32_e64 v0, v13, 0, s[64:65]
	v_bfe_u32 v2, v0, 16, 1
	v_add3_u32 v0, v0, v2, s27
	ds_write_b16_d16_hi v141, v0 offset:54960
	v_cndmask_b32_e64 v0, v14, 0, s[66:67]
	v_bfe_u32 v2, v0, 16, 1
	v_add3_u32 v0, v0, v2, s27
	ds_write_b16_d16_hi v141, v0 offset:55680
	v_cndmask_b32_e64 v0, v15, 0, s[68:69]
	v_bfe_u32 v2, v0, 16, 1
	v_add3_u32 v0, v0, v2, s27
	ds_write_b16_d16_hi v141, v0 offset:55824
	v_cndmask_b32_e64 v0, v16, 0, s[70:71]
	v_bfe_u32 v2, v0, 16, 1
	v_add3_u32 v0, v0, v2, s27
	ds_write_b16_d16_hi v141, v0 offset:55968
	v_cndmask_b32_e64 v0, v17, 0, s[72:73]
	v_bfe_u32 v2, v0, 16, 1
	v_add3_u32 v0, v0, v2, s27
	ds_write_b16_d16_hi v141, v0 offset:56112

.LBB0_675:
	s_or_b64 exec, exec, s[24:25]
	s_and_b64 s[10:11], vcc, exec
	s_movk_i32 s4, 0x68
	s_cselect_b32 s4, s4, 0x78
	s_add_u32 s10, s8, s4
	s_addc_u32 s11, s9, 0
	s_waitcnt lgkmcnt(0)
	s_barrier
	s_load_dwordx2 s[10:11], s[10:11], 0x0
	v_and_b32_e32 v3, 63, v2
	v_lshlrev_b32_e32 v0, 2, v3
	s_waitcnt lgkmcnt(0)
	s_add_u32 s4, s10, s22
	s_addc_u32 s5, s11, s23
	s_lshl_b32 s7, s6, 2
	s_add_u32 s10, s4, s7
	s_addc_u32 s11, s5, 0
	v_lshl_add_u64 v[8:9], s[10:11], 0, v[0:1]
	v_add_co_u32_e64 v34, s[40:41], s37, v8
	s_and_b64 s[14:15], vcc, exec
	s_nop 0
	v_addc_co_u32_e64 v35, s[40:41], 0, v9, s[40:41]
	s_movk_i32 s4, 0x70
	v_add_co_u32_e64 v36, s[40:41], s85, v8
	s_cselect_b32 s4, s4, 0x80
	s_nop 0
	v_addc_co_u32_e64 v37, s[40:41], 0, v9, s[40:41]
	s_add_u32 s14, s8, s4
	v_add_co_u32_e64 v26, s[40:41], s68, v8
	s_addc_u32 s15, s9, 0
	global_load_dword v6, v[36:37], off
	global_load_dword v7, v[36:37], off offset:1024
	global_load_dword v4, v[36:37], off offset:2048
	global_load_dword v5, v[36:37], off offset:3072
	v_addc_co_u32_e64 v27, s[40:41], 0, v9, s[40:41]
	global_load_dword v12, v[34:35], off offset:2048
	global_load_dword v13, v[34:35], off offset:3072
	global_load_dword v8, v[26:27], off
	s_load_dwordx2 s[14:15], s[14:15], 0x0
	v_readlane_b32 s4, v254, 41
	s_or_b32 s4, s6, s4
	global_load_dword v9, v[26:27], off offset:1024
	global_load_dword v10, v[26:27], off offset:2048
	global_load_dword v11, v[26:27], off offset:3072
	v_or_b32_e32 v26, s4, v3
	v_mov_b32_e32 v27, v1
	s_waitcnt lgkmcnt(0)
	v_lshl_add_u64 v[26:27], v[26:27], 2, s[14:15]
	global_load_dword v26, v[26:27], off
	s_nop 0
	global_load_dword v29, v0, s[10:11]
	global_load_dword v30, v0, s[10:11] offset:1024
	global_load_dword v31, v0, s[10:11] offset:2048
	global_load_dword v32, v0, s[10:11] offset:3072
	global_load_dword v28, v[36:37], off offset:-4096
	global_load_dword v27, v[34:35], off offset:1024
	v_ashrrev_i32_e32 v3, 6, v2
	v_lshl_add_u32 v25, v3, 9, 0
	ds_read_b128 v[34:37], v25 offset:27664
	ds_read_b128 v[38:41], v25 offset:27680
	ds_read_b128 v[42:45], v25 offset:27696
	ds_read_b128 v[46:49], v25 offset:27648
	s_mov_b32 s4, 0x3d800000
	v_lshl_add_u32 v2, v2, 2, 0
	v_add_u32_e32 v0, 0, v0
	v_readlane_b32 s5, v254, 42
	s_waitcnt vmcnt(15) lgkmcnt(2)
	v_pk_mul_f32 v[38:39], v[6:7], v[38:39]
	s_waitcnt vmcnt(13)
	v_pk_mul_f32 v[40:41], v[4:5], v[40:41]
	s_waitcnt vmcnt(11)
	v_pk_mul_f32 v[36:37], v[12:13], v[36:37]
	s_waitcnt vmcnt(9) lgkmcnt(1)
	v_pk_mul_f32 v[42:43], v[8:9], v[42:43]
	s_waitcnt vmcnt(5) lgkmcnt(0)
	v_fma_f32 v33, v29, v46, v26
	s_waitcnt vmcnt(4)
	v_fmac_f32_e32 v33, v30, v47
	s_waitcnt vmcnt(3)
	v_fmac_f32_e32 v33, v31, v48
	s_waitcnt vmcnt(2)
	v_fmac_f32_e32 v33, v32, v49
	s_waitcnt vmcnt(1)
	v_fmac_f32_e32 v33, v28, v34
	s_waitcnt vmcnt(0)
	v_fmac_f32_e32 v33, v27, v35
	v_add_f32_e32 v33, v33, v36
	v_add_f32_e32 v33, v33, v37
	v_add_f32_e32 v33, v33, v38
	v_add_f32_e32 v33, v33, v39
	v_add_f32_e32 v33, v33, v40
	v_add_f32_e32 v33, v33, v41
	v_add_f32_e32 v33, v33, v42
	v_pk_mul_f32 v[44:45], v[10:11], v[44:45]
	v_add_f32_e32 v33, v33, v43
	v_add_f32_e32 v33, v33, v44
	v_add_f32_e32 v33, v33, v45
	v_mul_f32_e64 v34, |v33|, s90
	v_exp_f32_e32 v38, v34
	v_min_f32_e32 v33, 0, v33
	v_add_f32_e32 v36, 1.0, v38
	v_add_f32_e32 v37, -1.0, v36
	v_frexp_mant_f32_e32 v39, v36
	v_cvt_f64_f32_e32 v[34:35], v36
	v_sub_f32_e32 v40, v37, v36
	v_frexp_exp_i32_f64_e32 v34, v[34:35]
	v_cmp_gt_f32_e32 vcc, s36, v39
	v_sub_f32_e32 v37, v38, v37
	v_add_f32_e32 v35, 1.0, v40
	v_subbrev_co_u32_e32 v34, vcc, 0, v34, vcc
	v_add_f32_e32 v35, v37, v35
	v_sub_u32_e32 v37, 0, v34
	v_cvt_f32_i32_e32 v34, v34
	v_ldexp_f32 v36, v36, v37
	v_ldexp_f32 v35, v35, v37
	v_add_f32_e32 v37, -1.0, v36
	v_add_f32_e32 v39, 1.0, v36
	v_add_f32_e32 v40, 1.0, v37
	v_add_f32_e32 v41, -1.0, v39
	v_sub_f32_e32 v40, v36, v40
	v_sub_f32_e32 v36, v36, v41
	v_mul_f32_e32 v41, 0x3f317218, v34
	v_add_f32_e32 v40, v35, v40
	v_add_f32_e32 v35, v35, v36
	v_fma_f32 v36, v34, s78, -v41
	v_add_f32_e32 v42, v37, v40
	v_add_f32_e32 v43, v39, v35
	v_fmac_f32_e32 v36, 0xb102e308, v34
	v_sub_f32_e32 v34, v42, v37
	v_sub_f32_e32 v37, v43, v39
	v_rcp_f32_e32 v39, v43
	v_add_f32_e32 v44, v41, v36
	v_sub_f32_e32 v35, v35, v37
	v_sub_f32_e32 v37, v44, v41
	v_sub_f32_e32 v36, v36, v37
	v_mul_f32_e32 v37, v42, v39
	v_sub_f32_e32 v34, v40, v34
	v_mul_f32_e32 v40, v43, v37
	v_fma_f32 v41, v37, v43, -v40
	v_fmac_f32_e32 v41, v37, v35
	v_add_f32_e32 v45, v40, v41
	v_sub_f32_e32 v46, v42, v45
	v_sub_f32_e32 v40, v45, v40
	v_sub_f32_e32 v42, v42, v46
	v_sub_f32_e32 v40, v40, v41
	v_sub_f32_e32 v41, v42, v45
	v_add_f32_e32 v34, v34, v41
	v_add_f32_e32 v34, v40, v34
	v_add_f32_e32 v40, v46, v34
	v_mul_f32_e32 v41, v39, v40
	v_sub_f32_e32 v42, v46, v40
	v_mul_f32_e32 v45, v43, v41
	v_add_f32_e32 v34, v34, v42
	v_add_f32_e32 v42, v37, v41
	v_fma_f32 v43, v41, v43, -v45
	v_sub_f32_e32 v37, v42, v37
	v_fmac_f32_e32 v43, v41, v35
	v_sub_f32_e32 v35, v41, v37
	v_add_f32_e32 v37, v45, v43
	v_sub_f32_e32 v41, v37, v45
	v_sub_f32_e32 v45, v40, v37
	v_sub_f32_e32 v40, v40, v45
	v_sub_f32_e32 v37, v40, v37
	v_sub_f32_e32 v41, v41, v43
	v_add_f32_e32 v34, v34, v37
	v_add_f32_e32 v34, v41, v34
	v_add_f32_e32 v34, v45, v34
	v_mul_f32_e32 v34, v39, v34
	v_add_f32_e32 v34, v35, v34
	v_add_f32_e32 v35, v42, v34
	v_mul_f32_e32 v37, v35, v35
	v_fmamk_f32 v41, v37, 0x3e9b6dac, v204
	v_sub_f32_e32 v39, v35, v42
	v_ldexp_f32 v40, v35, 1
	v_mul_f32_e32 v35, v35, v37
	v_fmaak_f32 v37, v37, v41, 0x3f2aaada
	v_mul_f32_e32 v35, v35, v37
	v_add_f32_e32 v37, v40, v35
	v_sub_f32_e32 v34, v34, v39
	v_sub_f32_e32 v39, v37, v40
	v_ldexp_f32 v34, v34, 1
	v_sub_f32_e32 v35, v35, v39
	v_add_f32_e32 v34, v34, v35
	v_add_f32_e32 v35, v37, v34
	v_sub_f32_e32 v37, v35, v37
	v_add_f32_e32 v39, v44, v35
	v_sub_f32_e32 v34, v34, v37
	v_sub_f32_e32 v37, v39, v44
	v_sub_f32_e32 v40, v39, v37
	v_sub_f32_e32 v35, v35, v37
	v_add_f32_e32 v37, v36, v34
	v_sub_f32_e32 v40, v44, v40
	v_add_f32_e32 v35, v35, v40
	v_sub_f32_e32 v40, v37, v36
	v_sub_f32_e32 v41, v37, v40
	v_sub_f32_e32 v36, v36, v41
	v_sub_f32_e32 v34, v34, v40
	v_add_f32_e32 v35, v37, v35
	v_add_f32_e32 v34, v34, v36
	v_add_f32_e32 v36, v39, v35
	v_sub_f32_e32 v37, v36, v39
	v_sub_f32_e32 v35, v35, v37
	v_add_f32_e32 v34, v34, v35
	v_add_f32_e32 v34, v36, v34
	v_cmp_neq_f32_e32 vcc, s79, v38
	s_nop 1
	v_cndmask_b32_e32 v34, v211, v34, vcc
	v_cmp_ngt_f32_e32 vcc, -1.0, v38
	s_nop 1
	v_cndmask_b32_e32 v39, v212, v34, vcc
	ds_read_b128 v[34:37], v25 offset:27712
	v_cmp_neq_f32_e32 vcc, -1.0, v38
	s_nop 1
	v_cndmask_b32_e32 v39, v213, v39, vcc
	v_cmp_lt_f32_e64 vcc, |v38|, s2
	s_nop 1
	v_cndmask_b32_e32 v42, v39, v38, vcc
	ds_read_b128 v[38:41], v25 offset:27728
	s_waitcnt lgkmcnt(1)
	v_fma_f32 v43, v29, v34, v26
	v_fmac_f32_e32 v43, v30, v35
	v_fmac_f32_e32 v43, v31, v36
	v_fmac_f32_e32 v43, v32, v37
	ds_read_b128 v[34:37], v25 offset:27744
	s_waitcnt lgkmcnt(1)
	v_fmac_f32_e32 v43, v28, v38
	v_fmac_f32_e32 v43, v27, v39
	v_pk_mul_f32 v[38:39], v[12:13], v[40:41]
	v_sub_f32_e32 v33, v33, v42
	v_add_f32_e32 v38, v43, v38
	v_add_f32_e32 v43, v38, v39
	ds_read_b128 v[38:41], v25 offset:27760
	s_waitcnt lgkmcnt(1)
	v_pk_mul_f32 v[34:35], v[6:7], v[34:35]
	v_fma_f32 v33, v33, s4, 0
	v_add_f32_e32 v34, v43, v34
	v_add_f32_e32 v43, v34, v35
	v_pk_mul_f32 v[34:35], v[4:5], v[36:37]
	s_nop 0
	v_add_f32_e32 v34, v43, v34
	v_add_f32_e32 v36, v34, v35
	s_waitcnt lgkmcnt(0)
	v_pk_mul_f32 v[34:35], v[8:9], v[38:39]
	s_nop 0
	v_add_f32_e32 v34, v36, v34
	v_add_f32_e32 v36, v34, v35
	v_pk_mul_f32 v[34:35], v[10:11], v[40:41]
	s_nop 0
	v_add_f32_e32 v34, v36, v34
	v_add_f32_e32 v34, v34, v35
	v_mul_f32_e64 v35, |v34|, s90
	v_exp_f32_e32 v38, v35
	v_min_f32_e32 v42, 0, v34
	v_add_f32_e32 v36, 1.0, v38
	v_add_f32_e32 v34, -1.0, v36
	v_sub_f32_e32 v35, v34, v36
	v_add_f32_e32 v35, 1.0, v35
	v_sub_f32_e32 v34, v38, v34
	v_add_f32_e32 v37, v34, v35
	v_frexp_mant_f32_e32 v39, v36
	v_cvt_f64_f32_e32 v[34:35], v36
	v_frexp_exp_i32_f64_e32 v34, v[34:35]
	v_cmp_gt_f32_e32 vcc, s36, v39
	s_nop 1
	v_subbrev_co_u32_e32 v34, vcc, 0, v34, vcc
	v_sub_u32_e32 v35, 0, v34
	v_ldexp_f32 v36, v36, v35
	v_ldexp_f32 v35, v37, v35
	v_add_f32_e32 v37, -1.0, v36
	v_add_f32_e32 v41, 1.0, v36
	v_add_f32_e32 v39, 1.0, v37
	v_add_f32_e32 v43, -1.0, v41
	v_sub_f32_e32 v39, v36, v39
	v_sub_f32_e32 v36, v36, v43
	v_add_f32_e32 v39, v35, v39
	v_add_f32_e32 v35, v35, v36
	v_add_f32_e32 v36, v41, v35
	v_rcp_f32_e32 v43, v36
	v_add_f32_e32 v40, v37, v39
	v_sub_f32_e32 v37, v40, v37
	v_sub_f32_e32 v37, v39, v37
	v_sub_f32_e32 v39, v36, v41
	v_sub_f32_e32 v35, v35, v39
	v_mul_f32_e32 v39, v40, v43
	v_mul_f32_e32 v41, v36, v39
	v_fma_f32 v44, v39, v36, -v41
	v_fmac_f32_e32 v44, v39, v35
	v_add_f32_e32 v45, v41, v44
	v_sub_f32_e32 v46, v40, v45
	v_sub_f32_e32 v40, v40, v46
	v_sub_f32_e32 v41, v45, v41
	v_sub_f32_e32 v40, v40, v45
	v_add_f32_e32 v37, v37, v40
	v_sub_f32_e32 v40, v41, v44
	v_add_f32_e32 v37, v40, v37
	v_add_f32_e32 v40, v46, v37
	v_mul_f32_e32 v41, v43, v40
	v_mul_f32_e32 v44, v36, v41
	v_fma_f32 v36, v41, v36, -v44
	v_fmac_f32_e32 v36, v41, v35
	v_sub_f32_e32 v35, v46, v40
	v_add_f32_e32 v35, v37, v35
	v_add_f32_e32 v37, v44, v36
	v_sub_f32_e32 v45, v40, v37
	v_sub_f32_e32 v40, v40, v45
	v_sub_f32_e32 v44, v37, v44
	v_sub_f32_e32 v37, v40, v37
	v_add_f32_e32 v35, v35, v37
	v_sub_f32_e32 v36, v44, v36
	v_cvt_f32_i32_e32 v34, v34
	v_add_f32_e32 v35, v36, v35
	v_add_f32_e32 v36, v39, v41
	v_add_f32_e32 v35, v45, v35
	v_sub_f32_e32 v37, v36, v39
	v_mul_f32_e32 v35, v43, v35
	v_sub_f32_e32 v37, v41, v37
	v_add_f32_e32 v35, v37, v35
	v_mul_f32_e32 v41, 0x3f317218, v34
	v_add_f32_e32 v37, v36, v35
	v_fma_f32 v43, v34, s78, -v41
	v_mul_f32_e32 v39, v37, v37
	v_fmac_f32_e32 v43, 0xb102e308, v34
	v_sub_f32_e32 v34, v37, v36
	v_fmamk_f32 v40, v39, 0x3e9b6dac, v204
	v_sub_f32_e32 v34, v35, v34
	v_add_f32_e32 v35, v41, v43
	v_fmaak_f32 v40, v39, v40, 0x3f2aaada
	v_sub_f32_e32 v36, v35, v41
	v_ldexp_f32 v41, v37, 1
	v_mul_f32_e32 v37, v37, v39
	v_mul_f32_e32 v37, v37, v40
	v_add_f32_e32 v39, v41, v37
	v_sub_f32_e32 v40, v39, v41
	v_ldexp_f32 v34, v34, 1
	v_sub_f32_e32 v37, v37, v40
	v_add_f32_e32 v34, v34, v37
	v_add_f32_e32 v37, v39, v34
	v_sub_f32_e32 v39, v37, v39
	v_sub_f32_e32 v34, v34, v39
	v_add_f32_e32 v39, v35, v37
	v_sub_f32_e32 v40, v39, v35
	v_sub_f32_e32 v41, v39, v40
	v_sub_f32_e32 v36, v43, v36
	v_sub_f32_e32 v35, v35, v41
	v_sub_f32_e32 v37, v37, v40
	v_add_f32_e32 v35, v37, v35
	v_add_f32_e32 v37, v36, v34
	v_sub_f32_e32 v40, v37, v36
	v_sub_f32_e32 v41, v37, v40
	v_sub_f32_e32 v36, v36, v41
	v_sub_f32_e32 v34, v34, v40
	v_add_f32_e32 v35, v37, v35
	v_add_f32_e32 v34, v34, v36
	v_add_f32_e32 v36, v39, v35
	v_sub_f32_e32 v37, v36, v39
	v_sub_f32_e32 v35, v35, v37
	v_add_f32_e32 v34, v34, v35
	v_add_f32_e32 v34, v36, v34
	v_cmp_neq_f32_e32 vcc, s79, v38
	s_nop 1
	v_cndmask_b32_e32 v34, v211, v34, vcc
	v_cmp_ngt_f32_e32 vcc, -1.0, v38
	s_nop 1
	v_cndmask_b32_e32 v39, v212, v34, vcc
	ds_read_b128 v[34:37], v25 offset:27776
	v_cmp_neq_f32_e32 vcc, -1.0, v38
	s_nop 1
	v_cndmask_b32_e32 v39, v213, v39, vcc
	v_cmp_lt_f32_e64 vcc, |v38|, s2
	s_nop 1
	v_cndmask_b32_e32 v43, v39, v38, vcc
	ds_read_b128 v[38:41], v25 offset:27792
	s_waitcnt lgkmcnt(1)
	v_fma_f32 v44, v29, v34, v26
	v_fmac_f32_e32 v44, v30, v35
	v_fmac_f32_e32 v44, v31, v36
	v_fmac_f32_e32 v44, v32, v37
	ds_read_b128 v[34:37], v25 offset:27808
	s_waitcnt lgkmcnt(1)
	v_fmac_f32_e32 v44, v28, v38
	v_fmac_f32_e32 v44, v27, v39
	v_pk_mul_f32 v[38:39], v[12:13], v[40:41]
	s_nop 0
	v_add_f32_e32 v38, v44, v38
	v_add_f32_e32 v44, v38, v39
	ds_read_b128 v[38:41], v25 offset:27824
	s_waitcnt lgkmcnt(1)
	v_pk_mul_f32 v[34:35], v[6:7], v[34:35]
	s_nop 0
	v_add_f32_e32 v34, v44, v34
	v_add_f32_e32 v44, v34, v35
	v_pk_mul_f32 v[34:35], v[4:5], v[36:37]
	s_nop 0
	v_add_f32_e32 v34, v44, v34
	v_add_f32_e32 v36, v34, v35
	s_waitcnt lgkmcnt(0)
	v_pk_mul_f32 v[34:35], v[8:9], v[38:39]
	s_nop 0
	v_add_f32_e32 v34, v36, v34
	v_add_f32_e32 v36, v34, v35
	v_pk_mul_f32 v[34:35], v[10:11], v[40:41]
	s_nop 0
	v_add_f32_e32 v34, v36, v34
	v_add_f32_e32 v35, v34, v35
	v_mul_f32_e64 v34, |v35|, s90
	v_exp_f32_e32 v40, v34
	v_sub_f32_e32 v34, v42, v43
	v_min_f32_e32 v35, 0, v35
	v_fmamk_f32 v34, v34, 0x3d800000, v33
	v_add_f32_e32 v38, 1.0, v40
	v_add_f32_e32 v36, -1.0, v38
	v_sub_f32_e32 v37, v36, v38
	v_add_f32_e32 v37, 1.0, v37
	v_sub_f32_e32 v36, v40, v36
	v_add_f32_e32 v39, v36, v37
	v_frexp_mant_f32_e32 v41, v38
	v_cvt_f64_f32_e32 v[36:37], v38
	v_frexp_exp_i32_f64_e32 v36, v[36:37]
	v_cmp_gt_f32_e32 vcc, s36, v41
	s_nop 1
	v_subbrev_co_u32_e32 v36, vcc, 0, v36, vcc
	v_sub_u32_e32 v37, 0, v36
	v_ldexp_f32 v38, v38, v37
	v_ldexp_f32 v37, v39, v37
	v_add_f32_e32 v39, -1.0, v38
	v_add_f32_e32 v43, 1.0, v38
	v_add_f32_e32 v41, 1.0, v39
	v_add_f32_e32 v44, -1.0, v43
	v_sub_f32_e32 v41, v38, v41
	v_sub_f32_e32 v38, v38, v44
	v_add_f32_e32 v41, v37, v41
	v_add_f32_e32 v37, v37, v38
	v_add_f32_e32 v38, v43, v37
	v_rcp_f32_e32 v44, v38
	v_add_f32_e32 v42, v39, v41
	v_sub_f32_e32 v39, v42, v39
	v_sub_f32_e32 v39, v41, v39
	v_sub_f32_e32 v41, v38, v43
	v_sub_f32_e32 v37, v37, v41
	v_mul_f32_e32 v41, v42, v44
	v_mul_f32_e32 v43, v38, v41
	v_fma_f32 v45, v41, v38, -v43
	v_fmac_f32_e32 v45, v41, v37
	v_add_f32_e32 v46, v43, v45
	v_sub_f32_e32 v47, v42, v46
	v_sub_f32_e32 v42, v42, v47
	v_sub_f32_e32 v43, v46, v43
	v_sub_f32_e32 v42, v42, v46
	v_add_f32_e32 v39, v39, v42
	v_sub_f32_e32 v42, v43, v45
	v_add_f32_e32 v39, v42, v39
	v_add_f32_e32 v42, v47, v39
	v_mul_f32_e32 v43, v44, v42
	v_mul_f32_e32 v45, v38, v43
	v_fma_f32 v38, v43, v38, -v45
	v_fmac_f32_e32 v38, v43, v37
	v_sub_f32_e32 v37, v47, v42
	v_add_f32_e32 v37, v39, v37
	v_add_f32_e32 v39, v45, v38
	v_sub_f32_e32 v46, v42, v39
	v_sub_f32_e32 v42, v42, v46
	v_sub_f32_e32 v45, v39, v45
	v_sub_f32_e32 v39, v42, v39
	v_add_f32_e32 v37, v37, v39
	v_sub_f32_e32 v38, v45, v38
	v_cvt_f32_i32_e32 v36, v36
	v_add_f32_e32 v37, v38, v37
	v_add_f32_e32 v38, v41, v43
	v_add_f32_e32 v37, v46, v37
	v_sub_f32_e32 v39, v38, v41
	v_mul_f32_e32 v37, v44, v37
	v_sub_f32_e32 v39, v43, v39
	v_add_f32_e32 v37, v39, v37
	v_mul_f32_e32 v43, 0x3f317218, v36
	v_add_f32_e32 v39, v38, v37
	v_fma_f32 v44, v36, s78, -v43
	v_mul_f32_e32 v41, v39, v39
	v_fmac_f32_e32 v44, 0xb102e308, v36
	v_sub_f32_e32 v36, v39, v38
	v_fmamk_f32 v42, v41, 0x3e9b6dac, v204
	v_sub_f32_e32 v36, v37, v36
	v_add_f32_e32 v37, v43, v44
	v_fmaak_f32 v42, v41, v42, 0x3f2aaada
	v_sub_f32_e32 v38, v37, v43
	v_ldexp_f32 v43, v39, 1
	v_mul_f32_e32 v39, v39, v41
	v_mul_f32_e32 v39, v39, v42
	v_add_f32_e32 v41, v43, v39
	v_sub_f32_e32 v42, v41, v43
	v_ldexp_f32 v36, v36, 1
	v_sub_f32_e32 v39, v39, v42
	v_add_f32_e32 v36, v36, v39
	v_add_f32_e32 v39, v41, v36
	v_sub_f32_e32 v41, v39, v41
	v_sub_f32_e32 v36, v36, v41
	v_add_f32_e32 v41, v37, v39
	v_sub_f32_e32 v42, v41, v37
	v_sub_f32_e32 v43, v41, v42
	v_sub_f32_e32 v38, v44, v38
	v_sub_f32_e32 v37, v37, v43
	v_sub_f32_e32 v39, v39, v42
	v_add_f32_e32 v37, v39, v37
	v_add_f32_e32 v39, v38, v36
	v_sub_f32_e32 v42, v39, v38
	v_sub_f32_e32 v43, v39, v42
	v_sub_f32_e32 v38, v38, v43
	v_sub_f32_e32 v36, v36, v42
	v_add_f32_e32 v37, v39, v37
	v_add_f32_e32 v36, v36, v38
	v_add_f32_e32 v38, v41, v37
	v_sub_f32_e32 v39, v38, v41
	v_sub_f32_e32 v37, v37, v39
	v_add_f32_e32 v36, v36, v37
	v_add_f32_e32 v36, v38, v36
	v_cmp_neq_f32_e32 vcc, s79, v40
	s_nop 1
	v_cndmask_b32_e32 v36, v211, v36, vcc
	v_cmp_ngt_f32_e32 vcc, -1.0, v40
	s_nop 1
	v_cndmask_b32_e32 v41, v212, v36, vcc
	ds_read_b128 v[36:39], v25 offset:27840
	v_cmp_neq_f32_e32 vcc, -1.0, v40
	s_nop 1
	v_cndmask_b32_e32 v41, v213, v41, vcc
	v_cmp_lt_f32_e64 vcc, |v40|, s2
	s_nop 1
	v_cndmask_b32_e32 v44, v41, v40, vcc
	ds_read_b128 v[40:43], v25 offset:27856
	s_waitcnt lgkmcnt(1)
	v_fma_f32 v45, v29, v36, v26
	v_fmac_f32_e32 v45, v30, v37
	v_fmac_f32_e32 v45, v31, v38
	v_fmac_f32_e32 v45, v32, v39
	ds_read_b128 v[36:39], v25 offset:27872
	s_waitcnt lgkmcnt(1)
	v_fmac_f32_e32 v45, v28, v40
	v_fmac_f32_e32 v45, v27, v41
	v_pk_mul_f32 v[40:41], v[12:13], v[42:43]
	v_sub_f32_e32 v35, v35, v44
	v_add_f32_e32 v40, v45, v40
	v_add_f32_e32 v45, v40, v41
	ds_read_b128 v[40:43], v25 offset:27888
	s_waitcnt lgkmcnt(1)
	v_pk_mul_f32 v[36:37], v[6:7], v[36:37]
	v_fmamk_f32 v35, v35, 0x3d800000, v34
	v_add_f32_e32 v36, v45, v36
	v_add_f32_e32 v45, v36, v37
	v_pk_mul_f32 v[36:37], v[4:5], v[38:39]
	s_nop 0
	v_add_f32_e32 v36, v45, v36
	v_add_f32_e32 v38, v36, v37
	s_waitcnt lgkmcnt(0)
	v_pk_mul_f32 v[36:37], v[8:9], v[40:41]
	s_nop 0
	v_add_f32_e32 v36, v38, v36
	v_add_f32_e32 v38, v36, v37
	v_pk_mul_f32 v[36:37], v[10:11], v[42:43]
	s_nop 0
	v_add_f32_e32 v36, v38, v36
	v_add_f32_e32 v36, v36, v37
	v_mul_f32_e64 v37, |v36|, s90
	v_exp_f32_e32 v40, v37
	v_min_f32_e32 v44, 0, v36
	v_add_f32_e32 v38, 1.0, v40
	v_add_f32_e32 v36, -1.0, v38
	v_sub_f32_e32 v37, v36, v38
	v_add_f32_e32 v37, 1.0, v37
	v_sub_f32_e32 v36, v40, v36
	v_add_f32_e32 v39, v36, v37
	v_frexp_mant_f32_e32 v41, v38
	v_cvt_f64_f32_e32 v[36:37], v38
	v_frexp_exp_i32_f64_e32 v36, v[36:37]
	v_cmp_gt_f32_e32 vcc, s36, v41
	s_nop 1
	v_subbrev_co_u32_e32 v36, vcc, 0, v36, vcc
	v_sub_u32_e32 v37, 0, v36
	v_ldexp_f32 v38, v38, v37
	v_ldexp_f32 v37, v39, v37
	v_add_f32_e32 v39, -1.0, v38
	v_add_f32_e32 v43, 1.0, v38
	v_add_f32_e32 v41, 1.0, v39
	v_add_f32_e32 v45, -1.0, v43
	v_sub_f32_e32 v41, v38, v41
	v_sub_f32_e32 v38, v38, v45
	v_add_f32_e32 v41, v37, v41
	v_add_f32_e32 v37, v37, v38
	v_add_f32_e32 v38, v43, v37
	v_rcp_f32_e32 v45, v38
	v_add_f32_e32 v42, v39, v41
	v_sub_f32_e32 v39, v42, v39
	v_sub_f32_e32 v39, v41, v39
	v_sub_f32_e32 v41, v38, v43
	v_sub_f32_e32 v37, v37, v41
	v_mul_f32_e32 v41, v42, v45
	v_mul_f32_e32 v43, v38, v41
	v_fma_f32 v46, v41, v38, -v43
	v_fmac_f32_e32 v46, v41, v37
	v_add_f32_e32 v47, v43, v46
	v_sub_f32_e32 v48, v42, v47
	v_sub_f32_e32 v42, v42, v48
	v_sub_f32_e32 v43, v47, v43
	v_sub_f32_e32 v42, v42, v47
	v_add_f32_e32 v39, v39, v42
	v_sub_f32_e32 v42, v43, v46
	v_add_f32_e32 v39, v42, v39
	v_add_f32_e32 v42, v48, v39
	v_mul_f32_e32 v43, v45, v42
	v_mul_f32_e32 v46, v38, v43
	v_fma_f32 v38, v43, v38, -v46
	v_fmac_f32_e32 v38, v43, v37
	v_sub_f32_e32 v37, v48, v42
	v_add_f32_e32 v37, v39, v37
	v_add_f32_e32 v39, v46, v38
	v_sub_f32_e32 v47, v42, v39
	v_sub_f32_e32 v42, v42, v47
	v_sub_f32_e32 v46, v39, v46
	v_sub_f32_e32 v39, v42, v39
	v_add_f32_e32 v37, v37, v39
	v_sub_f32_e32 v38, v46, v38
	v_cvt_f32_i32_e32 v36, v36
	v_add_f32_e32 v37, v38, v37
	v_add_f32_e32 v38, v41, v43
	v_add_f32_e32 v37, v47, v37
	v_sub_f32_e32 v39, v38, v41
	v_mul_f32_e32 v37, v45, v37
	v_sub_f32_e32 v39, v43, v39
	v_add_f32_e32 v37, v39, v37
	v_mul_f32_e32 v43, 0x3f317218, v36
	v_add_f32_e32 v39, v38, v37
	v_fma_f32 v45, v36, s78, -v43
	v_mul_f32_e32 v41, v39, v39
	v_fmac_f32_e32 v45, 0xb102e308, v36
	v_sub_f32_e32 v36, v39, v38
	v_fmamk_f32 v42, v41, 0x3e9b6dac, v204
	v_sub_f32_e32 v36, v37, v36
	v_add_f32_e32 v37, v43, v45
	v_fmaak_f32 v42, v41, v42, 0x3f2aaada
	v_sub_f32_e32 v38, v37, v43
	v_ldexp_f32 v43, v39, 1
	v_mul_f32_e32 v39, v39, v41
	v_mul_f32_e32 v39, v39, v42
	v_add_f32_e32 v41, v43, v39
	v_sub_f32_e32 v42, v41, v43
	v_ldexp_f32 v36, v36, 1
	v_sub_f32_e32 v39, v39, v42
	v_add_f32_e32 v36, v36, v39
	v_add_f32_e32 v39, v41, v36
	v_sub_f32_e32 v41, v39, v41
	v_sub_f32_e32 v36, v36, v41
	v_add_f32_e32 v41, v37, v39
	v_sub_f32_e32 v42, v41, v37
	v_sub_f32_e32 v43, v41, v42
	v_sub_f32_e32 v38, v45, v38
	v_sub_f32_e32 v37, v37, v43
	v_sub_f32_e32 v39, v39, v42
	v_add_f32_e32 v37, v39, v37
	v_add_f32_e32 v39, v38, v36
	v_sub_f32_e32 v42, v39, v38
	v_sub_f32_e32 v43, v39, v42
	v_sub_f32_e32 v38, v38, v43
	v_sub_f32_e32 v36, v36, v42
	v_add_f32_e32 v37, v39, v37
	v_add_f32_e32 v36, v36, v38
	v_add_f32_e32 v38, v41, v37
	v_sub_f32_e32 v39, v38, v41
	v_sub_f32_e32 v37, v37, v39
	v_add_f32_e32 v36, v36, v37
	v_add_f32_e32 v36, v38, v36
	v_cmp_neq_f32_e32 vcc, s79, v40
	s_nop 1
	v_cndmask_b32_e32 v36, v211, v36, vcc
	v_cmp_ngt_f32_e32 vcc, -1.0, v40
	s_nop 1
	v_cndmask_b32_e32 v41, v212, v36, vcc
	ds_read_b128 v[36:39], v25 offset:27904
	v_cmp_neq_f32_e32 vcc, -1.0, v40
	s_nop 1
	v_cndmask_b32_e32 v41, v213, v41, vcc
	v_cmp_lt_f32_e64 vcc, |v40|, s2
	s_nop 1
	v_cndmask_b32_e32 v45, v41, v40, vcc
	ds_read_b128 v[40:43], v25 offset:27920
	s_waitcnt lgkmcnt(1)
	v_fma_f32 v46, v29, v36, v26
	v_fmac_f32_e32 v46, v30, v37
	v_fmac_f32_e32 v46, v31, v38
	v_fmac_f32_e32 v46, v32, v39
	ds_read_b128 v[36:39], v25 offset:27936
	s_waitcnt lgkmcnt(1)
	v_fmac_f32_e32 v46, v28, v40
	v_fmac_f32_e32 v46, v27, v41
	v_pk_mul_f32 v[40:41], v[12:13], v[42:43]
	s_nop 0
	v_add_f32_e32 v40, v46, v40
	v_add_f32_e32 v46, v40, v41
	ds_read_b128 v[40:43], v25 offset:27952
	s_waitcnt lgkmcnt(1)
	v_pk_mul_f32 v[36:37], v[6:7], v[36:37]
	s_nop 0
	v_add_f32_e32 v36, v46, v36
	v_add_f32_e32 v46, v36, v37
	v_pk_mul_f32 v[36:37], v[4:5], v[38:39]
	s_nop 0
	v_add_f32_e32 v36, v46, v36
	v_add_f32_e32 v38, v36, v37
	s_waitcnt lgkmcnt(0)
	v_pk_mul_f32 v[36:37], v[8:9], v[40:41]
	s_nop 0
	v_add_f32_e32 v36, v38, v36
	v_add_f32_e32 v38, v36, v37
	v_pk_mul_f32 v[36:37], v[10:11], v[42:43]
	s_nop 0
	v_add_f32_e32 v36, v38, v36
	v_add_f32_e32 v37, v36, v37
	v_mul_f32_e64 v36, |v37|, s90
	v_exp_f32_e32 v42, v36
	v_sub_f32_e32 v36, v44, v45
	v_min_f32_e32 v37, 0, v37
	v_fmamk_f32 v36, v36, 0x3d800000, v35
	v_add_f32_e32 v40, 1.0, v42
	v_add_f32_e32 v38, -1.0, v40
	v_sub_f32_e32 v39, v38, v40
	v_add_f32_e32 v39, 1.0, v39
	v_sub_f32_e32 v38, v42, v38
	v_add_f32_e32 v41, v38, v39
	v_frexp_mant_f32_e32 v43, v40
	v_cvt_f64_f32_e32 v[38:39], v40
	v_frexp_exp_i32_f64_e32 v38, v[38:39]
	v_cmp_gt_f32_e32 vcc, s36, v43
	s_nop 1
	v_subbrev_co_u32_e32 v38, vcc, 0, v38, vcc
	v_sub_u32_e32 v39, 0, v38
	v_ldexp_f32 v40, v40, v39
	v_ldexp_f32 v39, v41, v39
	v_add_f32_e32 v41, -1.0, v40
	v_add_f32_e32 v45, 1.0, v40
	v_add_f32_e32 v43, 1.0, v41
	v_add_f32_e32 v46, -1.0, v45
	v_sub_f32_e32 v43, v40, v43
	v_sub_f32_e32 v40, v40, v46
	v_add_f32_e32 v43, v39, v43
	v_add_f32_e32 v39, v39, v40
	v_add_f32_e32 v40, v45, v39
	v_rcp_f32_e32 v46, v40
	v_add_f32_e32 v44, v41, v43
	v_sub_f32_e32 v41, v44, v41
	v_sub_f32_e32 v41, v43, v41
	v_sub_f32_e32 v43, v40, v45
	v_sub_f32_e32 v39, v39, v43
	v_mul_f32_e32 v43, v44, v46
	v_mul_f32_e32 v45, v40, v43
	v_fma_f32 v47, v43, v40, -v45
	v_fmac_f32_e32 v47, v43, v39
	v_add_f32_e32 v48, v45, v47
	v_sub_f32_e32 v49, v44, v48
	v_sub_f32_e32 v44, v44, v49
	v_sub_f32_e32 v45, v48, v45
	v_sub_f32_e32 v44, v44, v48
	v_add_f32_e32 v41, v41, v44
	v_sub_f32_e32 v44, v45, v47
	v_add_f32_e32 v41, v44, v41
	v_add_f32_e32 v44, v49, v41
	v_mul_f32_e32 v45, v46, v44
	v_mul_f32_e32 v47, v40, v45
	v_fma_f32 v40, v45, v40, -v47
	v_fmac_f32_e32 v40, v45, v39
	v_sub_f32_e32 v39, v49, v44
	v_add_f32_e32 v39, v41, v39
	v_add_f32_e32 v41, v47, v40
	v_sub_f32_e32 v48, v44, v41
	v_sub_f32_e32 v44, v44, v48
	v_sub_f32_e32 v47, v41, v47
	v_sub_f32_e32 v41, v44, v41
	v_add_f32_e32 v39, v39, v41
	v_sub_f32_e32 v40, v47, v40
	v_cvt_f32_i32_e32 v38, v38
	v_add_f32_e32 v39, v40, v39
	v_add_f32_e32 v40, v43, v45
	v_add_f32_e32 v39, v48, v39
	v_sub_f32_e32 v41, v40, v43
	v_mul_f32_e32 v39, v46, v39
	v_sub_f32_e32 v41, v45, v41
	v_add_f32_e32 v39, v41, v39
	v_mul_f32_e32 v45, 0x3f317218, v38
	v_add_f32_e32 v41, v40, v39
	v_fma_f32 v46, v38, s78, -v45
	v_mul_f32_e32 v43, v41, v41
	v_fmac_f32_e32 v46, 0xb102e308, v38
	v_sub_f32_e32 v38, v41, v40
	v_fmamk_f32 v44, v43, 0x3e9b6dac, v204
	v_sub_f32_e32 v38, v39, v38
	v_add_f32_e32 v39, v45, v46
	v_fmaak_f32 v44, v43, v44, 0x3f2aaada
	v_sub_f32_e32 v40, v39, v45
	v_ldexp_f32 v45, v41, 1
	v_mul_f32_e32 v41, v41, v43
	v_mul_f32_e32 v41, v41, v44
	v_add_f32_e32 v43, v45, v41
	v_sub_f32_e32 v44, v43, v45
	v_ldexp_f32 v38, v38, 1
	v_sub_f32_e32 v41, v41, v44
	v_add_f32_e32 v38, v38, v41
	v_add_f32_e32 v41, v43, v38
	v_sub_f32_e32 v43, v41, v43
	v_sub_f32_e32 v38, v38, v43
	v_add_f32_e32 v43, v39, v41
	v_sub_f32_e32 v44, v43, v39
	v_sub_f32_e32 v45, v43, v44
	v_sub_f32_e32 v40, v46, v40
	v_sub_f32_e32 v39, v39, v45
	v_sub_f32_e32 v41, v41, v44
	v_add_f32_e32 v39, v41, v39
	v_add_f32_e32 v41, v40, v38
	v_sub_f32_e32 v44, v41, v40
	v_sub_f32_e32 v45, v41, v44
	v_sub_f32_e32 v40, v40, v45
	v_sub_f32_e32 v38, v38, v44
	v_add_f32_e32 v39, v41, v39
	v_add_f32_e32 v38, v38, v40
	v_add_f32_e32 v40, v43, v39
	v_sub_f32_e32 v41, v40, v43
	v_sub_f32_e32 v39, v39, v41
	v_add_f32_e32 v38, v38, v39
	v_add_f32_e32 v38, v40, v38
	v_cmp_neq_f32_e32 vcc, s79, v42
	s_nop 1
	v_cndmask_b32_e32 v38, v211, v38, vcc
	v_cmp_ngt_f32_e32 vcc, -1.0, v42
	s_nop 1
	v_cndmask_b32_e32 v43, v212, v38, vcc
	ds_read_b128 v[38:41], v25 offset:27968
	v_cmp_neq_f32_e32 vcc, -1.0, v42
	s_nop 1
	v_cndmask_b32_e32 v43, v213, v43, vcc
	v_cmp_lt_f32_e64 vcc, |v42|, s2
	s_nop 1
	v_cndmask_b32_e32 v46, v43, v42, vcc
	ds_read_b128 v[42:45], v25 offset:27984
	s_waitcnt lgkmcnt(1)
	v_fma_f32 v47, v29, v38, v26
	v_fmac_f32_e32 v47, v30, v39
	v_fmac_f32_e32 v47, v31, v40
	v_fmac_f32_e32 v47, v32, v41
	ds_read_b128 v[38:41], v25 offset:28000
	s_waitcnt lgkmcnt(1)
	v_fmac_f32_e32 v47, v28, v42
	v_fmac_f32_e32 v47, v27, v43
	v_pk_mul_f32 v[42:43], v[12:13], v[44:45]
	v_sub_f32_e32 v37, v37, v46
	v_add_f32_e32 v42, v47, v42
	v_add_f32_e32 v47, v42, v43
	ds_read_b128 v[42:45], v25 offset:28016
	s_waitcnt lgkmcnt(1)
	v_pk_mul_f32 v[38:39], v[6:7], v[38:39]
	v_fmamk_f32 v37, v37, 0x3d800000, v36
	v_add_f32_e32 v38, v47, v38
	v_add_f32_e32 v47, v38, v39
	v_pk_mul_f32 v[38:39], v[4:5], v[40:41]
	s_nop 0
	v_add_f32_e32 v38, v47, v38
	v_add_f32_e32 v40, v38, v39
	s_waitcnt lgkmcnt(0)
	v_pk_mul_f32 v[38:39], v[8:9], v[42:43]
	s_nop 0
	v_add_f32_e32 v38, v40, v38
	v_add_f32_e32 v40, v38, v39
	v_pk_mul_f32 v[38:39], v[10:11], v[44:45]
	s_nop 0
	v_add_f32_e32 v38, v40, v38
	v_add_f32_e32 v38, v38, v39
	v_mul_f32_e64 v39, |v38|, s90
	v_exp_f32_e32 v52, v39
	v_min_f32_e32 v53, 0, v38
	v_add_f32_e32 v40, 1.0, v52
	v_add_f32_e32 v38, -1.0, v40
	v_sub_f32_e32 v39, v38, v40
	v_add_f32_e32 v39, 1.0, v39
	v_sub_f32_e32 v38, v52, v38
	v_add_f32_e32 v41, v38, v39
	v_frexp_mant_f32_e32 v42, v40
	v_cvt_f64_f32_e32 v[38:39], v40
	v_frexp_exp_i32_f64_e32 v38, v[38:39]
	v_cmp_gt_f32_e32 vcc, s36, v42
	s_nop 1
	v_subbrev_co_u32_e32 v46, vcc, 0, v38, vcc
	v_sub_u32_e32 v38, 0, v46
	v_ldexp_f32 v39, v40, v38
	v_add_f32_e32 v40, -1.0, v39
	v_add_f32_e32 v42, 1.0, v39
	v_ldexp_f32 v38, v41, v38
	v_add_f32_e32 v41, 1.0, v40
	v_add_f32_e32 v43, -1.0, v42
	v_sub_f32_e32 v41, v39, v41
	v_sub_f32_e32 v39, v39, v43
	v_add_f32_e32 v41, v38, v41
	v_add_f32_e32 v38, v38, v39
	v_add_f32_e32 v47, v42, v38
	v_rcp_f32_e32 v49, v47
	v_sub_f32_e32 v39, v47, v42
	v_sub_f32_e32 v48, v38, v39
	v_add_f32_e32 v39, v40, v41
	v_mul_f32_e32 v51, v39, v49
	v_sub_f32_e32 v38, v39, v40
	v_mul_f32_e32 v40, v47, v51
	v_fma_f32 v42, v51, v47, -v40
	v_fmac_f32_e32 v42, v51, v48
	v_sub_f32_e32 v50, v41, v38
	v_add_f32_e32 v38, v40, v42
	v_sub_f32_e32 v41, v39, v38
	v_pk_add_f32 v[44:45], v[38:39], v[40:41] neg_lo:[0,1] neg_hi:[0,1]
	v_mov_b32_e32 v43, v38
	v_pk_add_f32 v[38:39], v[44:45], v[42:43] neg_lo:[0,1] neg_hi:[0,1]
	v_cmp_neq_f32_e32 vcc, s79, v52
	v_add_f32_e32 v39, v50, v39
	v_add_f32_e32 v38, v38, v39
	v_add_f32_e32 v39, v41, v38
	v_mul_f32_e32 v50, v49, v39
	v_mul_f32_e32 v40, v47, v50
	v_fma_f32 v42, v50, v47, -v40
	v_fmac_f32_e32 v42, v50, v48
	v_sub_f32_e32 v41, v41, v39
	v_add_f32_e32 v47, v38, v41
	v_add_f32_e32 v38, v40, v42
	v_sub_f32_e32 v41, v39, v38
	v_pk_add_f32 v[44:45], v[38:39], v[40:41] neg_lo:[0,1] neg_hi:[0,1]
	v_mov_b32_e32 v43, v38
	v_pk_add_f32 v[38:39], v[44:45], v[42:43] neg_lo:[0,1] neg_hi:[0,1]
	s_nop 0
	v_add_f32_e32 v39, v47, v39
	v_add_f32_e32 v38, v38, v39
	v_add_f32_e32 v39, v51, v50
	v_add_f32_e32 v38, v41, v38
	v_sub_f32_e32 v40, v39, v51
	v_mul_f32_e32 v38, v49, v38
	v_sub_f32_e32 v40, v50, v40
	v_add_f32_e32 v40, v40, v38
	v_add_f32_e32 v42, v39, v40
	v_mul_f32_e32 v43, v42, v42
	v_fmamk_f32 v38, v43, 0x3e9b6dac, v204
	v_fmaak_f32 v175, v43, v38, 0x3f2aaada
	v_cvt_f32_i32_e32 v38, v46
	v_sub_f32_e32 v39, v42, v39
	v_sub_f32_e32 v39, v40, v39
	v_ldexp_f32 v44, v39, 1
	v_mul_f32_e32 v39, v42, v43
	v_ldexp_f32 v41, v42, 1
	v_pk_mul_f32 v[42:43], v[38:39], v[174:175]
	s_nop 0
	v_fma_f32 v40, v38, s78, -v42
	v_fmac_f32_e32 v40, 0xb102e308, v38
	v_pk_add_f32 v[38:39], v[42:43], v[40:41]
	s_nop 0
	v_sub_f32_e32 v41, v39, v41
	v_sub_f32_e32 v41, v43, v41
	v_add_f32_e32 v45, v44, v41
	v_mov_b32_e32 v44, v42
	v_pk_add_f32 v[42:43], v[38:39], v[42:43] neg_lo:[0,1] neg_hi:[0,1]
	v_pk_add_f32 v[46:47], v[38:39], v[44:45]
	v_mov_b32_e32 v41, v38
	v_mov_b32_e32 v43, v47
	v_pk_add_f32 v[48:49], v[40:41], v[42:43] neg_lo:[0,1] neg_hi:[0,1]
	v_pk_add_f32 v[40:41], v[40:41], v[42:43]
	v_mov_b32_e32 v44, v45
	v_pk_add_f32 v[42:43], v[40:41], v[38:39] op_sel:[1,0] op_sel_hi:[0,1] neg_lo:[0,1] neg_hi:[0,1]
	v_pk_add_f32 v[50:51], v[46:47], v[42:43] op_sel_hi:[1,0] neg_lo:[0,1] neg_hi:[0,1]
	v_mov_b32_e32 v46, v47
	v_mov_b32_e32 v47, v41
	v_pk_mov_b32 v[42:43], v[38:39], v[42:43] op_sel:[1,0]
	v_mov_b32_e32 v45, v38
	v_pk_add_f32 v[42:43], v[46:47], v[42:43] neg_lo:[0,1] neg_hi:[0,1]
	v_mov_b32_e32 v50, v48
	v_pk_add_f32 v[38:39], v[44:45], v[42:43] neg_lo:[0,1] neg_hi:[0,1]
	v_mov_b32_e32 v49, v41
	v_pk_add_f32 v[42:43], v[50:51], v[38:39]
	s_nop 0
	v_pk_add_f32 v[44:45], v[42:43], v[42:43] op_sel:[0,1] op_sel_hi:[1,0]
	s_nop 0
	v_pk_add_f32 v[40:41], v[40:41], v[44:45] op_sel:[1,0] op_sel_hi:[0,1]
	v_mov_b32_e32 v43, v40
	v_pk_add_f32 v[46:47], v[42:43], v[48:49] neg_lo:[0,1] neg_hi:[0,1]
	v_mov_b32_e32 v39, v44
	v_sub_f32_e32 v41, v42, v46
	v_pk_add_f32 v[38:39], v[38:39], v[46:47] neg_lo:[0,1] neg_hi:[0,1]
	v_sub_f32_e32 v41, v48, v41
	v_add_f32_e32 v38, v38, v41
	v_add_f32_e32 v38, v38, v39
	v_add_f32_e32 v38, v40, v38
	v_cndmask_b32_e32 v38, v211, v38, vcc
	v_cmp_ngt_f32_e32 vcc, -1.0, v52
	s_nop 1
	v_cndmask_b32_e32 v42, v212, v38, vcc
	ds_read_b128 v[38:41], v25 offset:28032
	v_cmp_neq_f32_e32 vcc, -1.0, v52
	s_nop 1
	v_cndmask_b32_e32 v42, v213, v42, vcc
	v_cmp_lt_f32_e64 vcc, |v52|, s2
	s_nop 1
	v_cndmask_b32_e32 v46, v42, v52, vcc
	ds_read_b128 v[42:45], v25 offset:28048
	s_waitcnt lgkmcnt(1)
	v_fma_f32 v47, v29, v38, v26
	v_fmac_f32_e32 v47, v30, v39
	v_fmac_f32_e32 v47, v31, v40
	v_fmac_f32_e32 v47, v32, v41
	ds_read_b128 v[38:41], v25 offset:28064
	s_waitcnt lgkmcnt(1)
	v_fmac_f32_e32 v47, v28, v42
	v_fmac_f32_e32 v47, v27, v43
	v_pk_mul_f32 v[42:43], v[12:13], v[44:45]
	s_nop 0
	v_add_f32_e32 v42, v47, v42
	v_add_f32_e32 v47, v42, v43
	ds_read_b128 v[42:45], v25 offset:28080
	s_waitcnt lgkmcnt(1)
	v_pk_mul_f32 v[38:39], v[6:7], v[38:39]
	s_nop 0
	v_add_f32_e32 v38, v47, v38
	v_add_f32_e32 v47, v38, v39
	v_pk_mul_f32 v[38:39], v[4:5], v[40:41]
	s_nop 0
	v_add_f32_e32 v38, v47, v38
	v_add_f32_e32 v40, v38, v39
	s_waitcnt lgkmcnt(0)
	v_pk_mul_f32 v[38:39], v[8:9], v[42:43]
	s_nop 0
	v_add_f32_e32 v38, v40, v38
	v_add_f32_e32 v40, v38, v39
	v_pk_mul_f32 v[38:39], v[10:11], v[44:45]
	s_nop 0
	v_add_f32_e32 v38, v40, v38
	v_add_f32_e32 v38, v38, v39
	v_mul_f32_e64 v39, |v38|, s90
	v_exp_f32_e32 v52, v39
	v_sub_f32_e32 v39, v53, v46
	v_min_f32_e32 v54, 0, v38
	v_fmamk_f32 v53, v39, 0x3d800000, v37
	v_add_f32_e32 v40, 1.0, v52
	v_add_f32_e32 v38, -1.0, v40
	v_sub_f32_e32 v39, v38, v40
	v_add_f32_e32 v39, 1.0, v39
	v_sub_f32_e32 v38, v52, v38
	v_add_f32_e32 v41, v38, v39
	v_frexp_mant_f32_e32 v42, v40
	v_cvt_f64_f32_e32 v[38:39], v40
	v_frexp_exp_i32_f64_e32 v38, v[38:39]
	v_cmp_gt_f32_e32 vcc, s36, v42
	s_nop 1
	v_subbrev_co_u32_e32 v46, vcc, 0, v38, vcc
	v_sub_u32_e32 v38, 0, v46
	v_ldexp_f32 v39, v40, v38
	v_add_f32_e32 v40, -1.0, v39
	v_add_f32_e32 v42, 1.0, v39
	v_ldexp_f32 v38, v41, v38
	v_add_f32_e32 v41, 1.0, v40
	v_add_f32_e32 v43, -1.0, v42
	v_sub_f32_e32 v41, v39, v41
	v_sub_f32_e32 v39, v39, v43
	v_add_f32_e32 v41, v38, v41
	v_add_f32_e32 v38, v38, v39
	v_add_f32_e32 v47, v42, v38
	v_rcp_f32_e32 v49, v47
	v_sub_f32_e32 v39, v47, v42
	v_sub_f32_e32 v48, v38, v39
	v_add_f32_e32 v39, v40, v41
	v_mul_f32_e32 v51, v39, v49
	v_sub_f32_e32 v38, v39, v40
	v_mul_f32_e32 v40, v47, v51
	v_fma_f32 v42, v51, v47, -v40
	v_fmac_f32_e32 v42, v51, v48
	v_sub_f32_e32 v50, v41, v38
	v_add_f32_e32 v38, v40, v42
	v_sub_f32_e32 v41, v39, v38
	v_pk_add_f32 v[44:45], v[38:39], v[40:41] neg_lo:[0,1] neg_hi:[0,1]
	v_mov_b32_e32 v43, v38
	v_pk_add_f32 v[38:39], v[44:45], v[42:43] neg_lo:[0,1] neg_hi:[0,1]
	v_cmp_neq_f32_e32 vcc, s79, v52
	v_add_f32_e32 v39, v50, v39
	v_add_f32_e32 v38, v38, v39
	v_add_f32_e32 v39, v41, v38
	v_mul_f32_e32 v50, v49, v39
	v_mul_f32_e32 v40, v47, v50
	v_fma_f32 v42, v50, v47, -v40
	v_fmac_f32_e32 v42, v50, v48
	v_sub_f32_e32 v41, v41, v39
	v_add_f32_e32 v47, v38, v41
	v_add_f32_e32 v38, v40, v42
	v_sub_f32_e32 v41, v39, v38
	v_pk_add_f32 v[44:45], v[38:39], v[40:41] neg_lo:[0,1] neg_hi:[0,1]
	v_mov_b32_e32 v43, v38
	v_pk_add_f32 v[38:39], v[44:45], v[42:43] neg_lo:[0,1] neg_hi:[0,1]
	s_nop 0
	v_add_f32_e32 v39, v47, v39
	v_add_f32_e32 v38, v38, v39
	v_add_f32_e32 v39, v51, v50
	v_add_f32_e32 v38, v41, v38
	v_sub_f32_e32 v40, v39, v51
	v_mul_f32_e32 v38, v49, v38
	v_sub_f32_e32 v40, v50, v40
	v_add_f32_e32 v40, v40, v38
	v_add_f32_e32 v42, v39, v40
	v_mul_f32_e32 v43, v42, v42
	v_fmamk_f32 v38, v43, 0x3e9b6dac, v204
	v_fmaak_f32 v175, v43, v38, 0x3f2aaada
	v_cvt_f32_i32_e32 v38, v46
	v_sub_f32_e32 v39, v42, v39
	v_sub_f32_e32 v39, v40, v39
	v_ldexp_f32 v44, v39, 1
	v_mul_f32_e32 v39, v42, v43
	v_ldexp_f32 v41, v42, 1
	v_pk_mul_f32 v[42:43], v[38:39], v[174:175]
	s_nop 0
	v_fma_f32 v40, v38, s78, -v42
	v_fmac_f32_e32 v40, 0xb102e308, v38
	v_pk_add_f32 v[38:39], v[42:43], v[40:41]
	s_nop 0
	v_sub_f32_e32 v41, v39, v41
	v_sub_f32_e32 v41, v43, v41
	v_add_f32_e32 v45, v44, v41
	v_mov_b32_e32 v44, v42
	v_pk_add_f32 v[42:43], v[38:39], v[42:43] neg_lo:[0,1] neg_hi:[0,1]
	v_pk_add_f32 v[46:47], v[38:39], v[44:45]
	v_mov_b32_e32 v41, v38
	v_mov_b32_e32 v43, v47
	v_pk_add_f32 v[48:49], v[40:41], v[42:43] neg_lo:[0,1] neg_hi:[0,1]
	v_pk_add_f32 v[40:41], v[40:41], v[42:43]
	v_mov_b32_e32 v44, v45
	v_pk_add_f32 v[42:43], v[40:41], v[38:39] op_sel:[1,0] op_sel_hi:[0,1] neg_lo:[0,1] neg_hi:[0,1]
	v_pk_add_f32 v[50:51], v[46:47], v[42:43] op_sel_hi:[1,0] neg_lo:[0,1] neg_hi:[0,1]
	v_mov_b32_e32 v46, v47
	v_mov_b32_e32 v47, v41
	v_pk_mov_b32 v[42:43], v[38:39], v[42:43] op_sel:[1,0]
	v_mov_b32_e32 v45, v38
	v_pk_add_f32 v[42:43], v[46:47], v[42:43] neg_lo:[0,1] neg_hi:[0,1]
	v_mov_b32_e32 v50, v48
	v_pk_add_f32 v[38:39], v[44:45], v[42:43] neg_lo:[0,1] neg_hi:[0,1]
	v_mov_b32_e32 v49, v41
	v_pk_add_f32 v[42:43], v[50:51], v[38:39]
	s_nop 0
	v_pk_add_f32 v[44:45], v[42:43], v[42:43] op_sel:[0,1] op_sel_hi:[1,0]
	s_nop 0
	v_pk_add_f32 v[40:41], v[40:41], v[44:45] op_sel:[1,0] op_sel_hi:[0,1]
	v_mov_b32_e32 v43, v40
	v_pk_add_f32 v[46:47], v[42:43], v[48:49] neg_lo:[0,1] neg_hi:[0,1]
	v_mov_b32_e32 v39, v44
	v_sub_f32_e32 v41, v42, v46
	v_pk_add_f32 v[38:39], v[38:39], v[46:47] neg_lo:[0,1] neg_hi:[0,1]
	v_sub_f32_e32 v41, v48, v41
	v_add_f32_e32 v38, v38, v41
	v_add_f32_e32 v38, v38, v39
	v_add_f32_e32 v38, v40, v38
	v_cndmask_b32_e32 v38, v211, v38, vcc
	v_cmp_ngt_f32_e32 vcc, -1.0, v52
	s_nop 1
	v_cndmask_b32_e32 v42, v212, v38, vcc
	ds_read_b128 v[38:41], v25 offset:28096
	v_cmp_neq_f32_e32 vcc, -1.0, v52
	s_nop 1
	v_cndmask_b32_e32 v42, v213, v42, vcc
	v_cmp_lt_f32_e64 vcc, |v52|, s2
	s_nop 1
	v_cndmask_b32_e32 v46, v42, v52, vcc
	ds_read_b128 v[42:45], v25 offset:28112
	s_waitcnt lgkmcnt(1)
	v_fmac_f32_e32 v26, v29, v38
	v_fmac_f32_e32 v26, v30, v39
	v_fmac_f32_e32 v26, v31, v40
	v_fmac_f32_e32 v26, v32, v41
	s_waitcnt lgkmcnt(0)
	v_fmac_f32_e32 v26, v28, v42
	ds_read_b128 v[28:31], v25 offset:28128
	ds_read_b128 v[38:41], v25 offset:28144
	v_fmac_f32_e32 v26, v27, v43
	v_pk_mul_f32 v[12:13], v[12:13], v[44:45]
	s_waitcnt lgkmcnt(1)
	v_pk_mul_f32 v[6:7], v[6:7], v[28:29]
	v_add_f32_e32 v12, v26, v12
	v_add_f32_e32 v12, v12, v13
	v_add_f32_e32 v6, v12, v6
	v_add_f32_e32 v6, v6, v7
	v_pk_mul_f32 v[4:5], v[4:5], v[30:31]
	s_nop 0
	v_add_f32_e32 v4, v6, v4
	v_add_f32_e32 v6, v4, v5
	s_waitcnt lgkmcnt(0)
	v_pk_mul_f32 v[4:5], v[8:9], v[38:39]
	s_nop 0
	v_add_f32_e32 v4, v6, v4
	v_add_f32_e32 v6, v4, v5
	v_pk_mul_f32 v[4:5], v[10:11], v[40:41]
	s_nop 0
	v_add_f32_e32 v4, v6, v4
	v_add_f32_e32 v4, v4, v5
	v_mul_f32_e64 v5, |v4|, s90
	v_exp_f32_e32 v25, v5
	v_sub_f32_e32 v5, v54, v46
	v_min_f32_e32 v31, 0, v4
	v_fmamk_f32 v30, v5, 0x3d800000, v53
	v_add_f32_e32 v6, 1.0, v25
	v_add_f32_e32 v4, -1.0, v6
	v_sub_f32_e32 v5, v4, v6
	v_add_f32_e32 v5, 1.0, v5
	v_sub_f32_e32 v4, v25, v4
	v_add_f32_e32 v7, v4, v5
	v_frexp_mant_f32_e32 v8, v6
	v_cvt_f64_f32_e32 v[4:5], v6
	v_frexp_exp_i32_f64_e32 v4, v[4:5]
	v_cmp_gt_f32_e32 vcc, s36, v8
	s_nop 1
	v_subbrev_co_u32_e32 v12, vcc, 0, v4, vcc
	v_sub_u32_e32 v4, 0, v12
	v_ldexp_f32 v5, v6, v4
	v_add_f32_e32 v6, -1.0, v5
	v_add_f32_e32 v8, 1.0, v5
	v_ldexp_f32 v4, v7, v4
	v_add_f32_e32 v7, 1.0, v6
	v_add_f32_e32 v9, -1.0, v8
	v_sub_f32_e32 v7, v5, v7
	v_sub_f32_e32 v5, v5, v9
	v_add_f32_e32 v7, v4, v7
	v_add_f32_e32 v4, v4, v5
	v_add_f32_e32 v13, v8, v4
	v_rcp_f32_e32 v27, v13
	v_sub_f32_e32 v5, v13, v8
	v_sub_f32_e32 v26, v4, v5
	v_add_f32_e32 v5, v6, v7
	v_mul_f32_e32 v29, v5, v27
	v_sub_f32_e32 v4, v5, v6
	v_mul_f32_e32 v6, v13, v29
	v_fma_f32 v8, v29, v13, -v6
	v_fmac_f32_e32 v8, v29, v26
	v_sub_f32_e32 v28, v7, v4
	v_add_f32_e32 v4, v6, v8
	v_sub_f32_e32 v7, v5, v4
	v_pk_add_f32 v[10:11], v[4:5], v[6:7] neg_lo:[0,1] neg_hi:[0,1]
	v_mov_b32_e32 v9, v4
	v_pk_add_f32 v[4:5], v[10:11], v[8:9] neg_lo:[0,1] neg_hi:[0,1]
	v_cmp_neq_f32_e32 vcc, s79, v25
	v_add_f32_e32 v5, v28, v5
	v_add_f32_e32 v4, v4, v5
	v_add_f32_e32 v5, v7, v4
	v_mul_f32_e32 v28, v27, v5
	v_mul_f32_e32 v6, v13, v28
	v_fma_f32 v8, v28, v13, -v6
	v_fmac_f32_e32 v8, v28, v26
	v_sub_f32_e32 v7, v7, v5
	v_add_f32_e32 v13, v4, v7
	v_add_f32_e32 v4, v6, v8
	v_sub_f32_e32 v7, v5, v4
	v_pk_add_f32 v[10:11], v[4:5], v[6:7] neg_lo:[0,1] neg_hi:[0,1]
	v_mov_b32_e32 v9, v4
	v_pk_add_f32 v[4:5], v[10:11], v[8:9] neg_lo:[0,1] neg_hi:[0,1]
	s_nop 0
	v_add_f32_e32 v5, v13, v5
	v_add_f32_e32 v4, v4, v5
	v_add_f32_e32 v5, v29, v28
	v_add_f32_e32 v4, v7, v4
	v_sub_f32_e32 v6, v5, v29
	v_mul_f32_e32 v4, v27, v4
	v_sub_f32_e32 v6, v28, v6
	v_add_f32_e32 v6, v6, v4
	v_add_f32_e32 v8, v5, v6
	v_mul_f32_e32 v9, v8, v8
	v_fmamk_f32 v4, v9, 0x3e9b6dac, v204
	v_fmaak_f32 v175, v9, v4, 0x3f2aaada
	v_cvt_f32_i32_e32 v4, v12
	v_sub_f32_e32 v5, v8, v5
	v_sub_f32_e32 v5, v6, v5
	v_ldexp_f32 v10, v5, 1
	v_mul_f32_e32 v5, v8, v9
	v_ldexp_f32 v7, v8, 1
	v_pk_mul_f32 v[8:9], v[4:5], v[174:175]
	s_nop 0
	v_fma_f32 v6, v4, s78, -v8
	v_fmac_f32_e32 v6, 0xb102e308, v4
	v_pk_add_f32 v[4:5], v[8:9], v[6:7]
	s_nop 0
	v_sub_f32_e32 v7, v5, v7
	v_sub_f32_e32 v7, v9, v7
	v_add_f32_e32 v11, v10, v7
	v_mov_b32_e32 v10, v8
	v_pk_add_f32 v[8:9], v[4:5], v[8:9] neg_lo:[0,1] neg_hi:[0,1]
	v_pk_add_f32 v[12:13], v[4:5], v[10:11]
	v_mov_b32_e32 v7, v4
	v_mov_b32_e32 v9, v13
	v_pk_add_f32 v[26:27], v[6:7], v[8:9] neg_lo:[0,1] neg_hi:[0,1]
	v_pk_add_f32 v[6:7], v[6:7], v[8:9]
	v_mov_b32_e32 v10, v11
	v_pk_add_f32 v[8:9], v[6:7], v[4:5] op_sel:[1,0] op_sel_hi:[0,1] neg_lo:[0,1] neg_hi:[0,1]
	v_pk_add_f32 v[28:29], v[12:13], v[8:9] op_sel_hi:[1,0] neg_lo:[0,1] neg_hi:[0,1]
	v_mov_b32_e32 v12, v13
	v_mov_b32_e32 v13, v7
	v_pk_mov_b32 v[8:9], v[4:5], v[8:9] op_sel:[1,0]
	v_mov_b32_e32 v11, v4
	v_pk_add_f32 v[8:9], v[12:13], v[8:9] neg_lo:[0,1] neg_hi:[0,1]
	v_mov_b32_e32 v28, v26
	v_pk_add_f32 v[4:5], v[10:11], v[8:9] neg_lo:[0,1] neg_hi:[0,1]
	v_mov_b32_e32 v27, v7
	v_pk_add_f32 v[8:9], v[28:29], v[4:5]
	s_nop 0
	v_pk_add_f32 v[10:11], v[8:9], v[8:9] op_sel:[0,1] op_sel_hi:[1,0]
	s_nop 0
	v_pk_add_f32 v[6:7], v[6:7], v[10:11] op_sel:[1,0] op_sel_hi:[0,1]
	v_mov_b32_e32 v9, v6
	v_pk_add_f32 v[12:13], v[8:9], v[26:27] neg_lo:[0,1] neg_hi:[0,1]
	v_mov_b32_e32 v5, v10
	v_sub_f32_e32 v7, v8, v12
	v_pk_add_f32 v[4:5], v[4:5], v[12:13] neg_lo:[0,1] neg_hi:[0,1]
	v_sub_f32_e32 v7, v26, v7
	v_add_f32_e32 v4, v4, v7
	v_add_f32_e32 v4, v4, v5
	v_add_f32_e32 v4, v6, v4
	v_cndmask_b32_e32 v4, v211, v4, vcc
	v_cmp_ngt_f32_e32 vcc, -1.0, v25
	s_nop 1
	v_cndmask_b32_e32 v4, v212, v4, vcc
	v_cmp_neq_f32_e32 vcc, -1.0, v25
	s_nop 1
	v_cndmask_b32_e32 v4, v213, v4, vcc
	v_cmp_lt_f32_e64 vcc, |v25|, s2
	s_nop 1
	v_cndmask_b32_e32 v4, v4, v25, vcc
	v_sub_f32_e32 v4, v31, v4
	v_fmamk_f32 v5, v4, 0x3d800000, v30
	ds_write_b32 v2, v5 offset:31744
	s_waitcnt lgkmcnt(0)
	s_barrier
	ds_read2st64_b32 v[6:7], v0 offset0:124 offset1:125
	ds_read2st64_b32 v[8:9], v0 offset0:126 offset1:127
	ds_read2st64_b32 v[10:11], v0 offset0:128 offset1:129
	ds_read2st64_b32 v[12:13], v0 offset0:130 offset1:131
	v_cmp_lt_i32_e32 vcc, 0, v3
	s_waitcnt lgkmcnt(3)
	v_add_f32_e32 v0, 0, v6
	s_waitcnt lgkmcnt(0)
	v_cndmask_b32_e32 v2, 0, v0, vcc
	v_add_f32_e32 v4, v7, v2
	v_cmp_lt_i32_e32 vcc, 1, v3
	v_add_f32_e32 v0, v0, v7
	v_add_f32_e32 v0, v0, v8
	v_cndmask_b32_e32 v2, v2, v4, vcc
	v_add_f32_e32 v4, v8, v2
	v_cmp_lt_i32_e32 vcc, 2, v3
	v_add_f32_e32 v0, v0, v9
	v_add_f32_e32 v0, v0, v10
	v_cndmask_b32_e32 v2, v2, v4, vcc
	v_add_f32_e32 v4, v9, v2
	v_cmp_lt_i32_e32 vcc, 3, v3
	v_add_f32_e32 v0, v0, v11
	v_lshlrev_b32_e32 v7, 16, v21
	v_cndmask_b32_e32 v2, v2, v4, vcc
	v_add_f32_e32 v4, v10, v2
	v_cmp_lt_i32_e32 vcc, 4, v3
	v_lshlrev_b32_e32 v9, 16, v22
	v_lshlrev_b32_e32 v8, 16, v17
	v_cndmask_b32_e32 v2, v2, v4, vcc
	v_add_f32_e32 v4, v11, v2
	v_cmp_lt_i32_e32 vcc, 5, v3
	v_lshlrev_b32_e32 v11, 16, v24
	v_lshlrev_b32_e32 v10, 16, v20
	v_cndmask_b32_e32 v2, v2, v4, vcc
	v_add_f32_e32 v4, v12, v2
	v_cmp_lt_i32_e32 vcc, 6, v3
	s_barrier
	s_nop 0
	v_cndmask_b32_e32 v2, v2, v4, vcc
	v_add_f32_e32 v4, v13, v2
	v_cmp_lt_i32_e32 vcc, 7, v3
	s_nop 1
	v_cndmask_b32_e32 v3, v2, v4, vcc
	v_add_f32_e32 v4, v0, v12
	v_mov_b32_e32 v2, v13
	v_add_f32_e32 v6, v33, v3
	v_add_f32_e32 v25, v34, v3
	v_add_f32_e32 v26, v35, v3
	v_add_f32_e32 v27, v36, v3
	v_add_f32_e32 v28, v3, v37
	v_add_f32_e32 v29, v3, v53
	v_add_f32_e32 v30, v3, v30
	v_pk_add_f32 v[2:3], v[4:5], v[2:3]
	v_mov_b32_e32 v80, v6
	v_mov_b32_e32 v81, v25
	v_mov_b32_e32 v82, v26
	v_mov_b32_e32 v83, v27
	v_mov_b32_e32 v84, v28
	v_mov_b32_e32 v85, v29
	v_mov_b32_e32 v86, v30
	v_mov_b32_e32 v87, v3
	s_load_dwordx2 s[100:101], s[8:9], 0x140
	v_lshlrev_b32_e32 v88, 5, v202
	s_lshl_b32 s98, s30, 14
	s_waitcnt lgkmcnt(0)
	s_add_u32 s100, s100, 0x4f28000
	s_addc_u32 s101, s101, 0
	s_add_u32 s100, s100, s98
	s_addc_u32 s101, s101, 0
	global_store_dwordx4 v88, v[80:83], s[100:101]
	global_store_dwordx4 v88, v[84:87], s[100:101] offset:16
	v_cmp_gt_i32_e32 vcc, 64, v18
	v_sub_f32_e32 v0, v2, v6
	v_mul_f32_e32 v0, 0x3fb8aa3b, v0
	v_exp_f32_e32 v4, v0
	v_sub_f32_e32 v0, v2, v25
	v_mul_f32_e32 v0, 0x3fb8aa3b, v0
	v_exp_f32_e32 v5, v0
	v_sub_f32_e32 v0, v2, v26
	v_lshlrev_b32_e32 v6, 16, v16
	v_mul_f32_e32 v0, 0x3fb8aa3b, v0
	v_pk_mul_f32 v[4:5], v[4:5], v[6:7]
	v_exp_f32_e32 v6, v0
	v_sub_f32_e32 v0, v2, v27
	v_mul_f32_e32 v0, 0x3fb8aa3b, v0
	v_exp_f32_e32 v7, v0
	v_sub_f32_e32 v0, v2, v28
	v_mul_f32_e32 v0, 0x3fb8aa3b, v0
	v_cvt_pk_bf16_f32 v4, v4, v5
	v_pk_mul_f32 v[6:7], v[6:7], v[8:9]
	v_exp_f32_e32 v8, v0
	v_sub_f32_e32 v0, v2, v29
	v_mul_f32_e32 v0, 0x3fb8aa3b, v0
	v_exp_f32_e32 v9, v0
	v_sub_f32_e32 v0, v2, v30
	v_cvt_pk_bf16_f32 v5, v6, v7
	v_lshlrev_b32_e32 v7, 16, v23
	v_lshlrev_b32_e32 v6, 16, v19
	v_mul_f32_e32 v0, 0x3fb8aa3b, v0
	v_pk_mul_f32 v[6:7], v[8:9], v[6:7]
	v_exp_f32_e32 v8, v0
	v_sub_f32_e32 v0, v2, v3
	v_mul_f32_e32 v0, 0x3fb8aa3b, v0
	v_exp_f32_e32 v9, v0
	v_mul_u32_u24_e32 v0, 0x90, v15
	v_lshlrev_b32_e32 v3, 4, v14
	v_cvt_pk_bf16_f32 v6, v6, v7
	v_pk_mul_f32 v[8:9], v[8:9], v[10:11]
	v_add3_u32 v0, 0, v0, v3
	v_cvt_pk_bf16_f32 v7, v8, v9
	ds_write_b128 v0, v[4:7]
	s_and_saveexec_b64 s[14:15], vcc
	s_cbranch_execz .LBB0_677
	v_mul_f32_e32 v0, 0x3fb8aa3b, v2
	s_lshl_b64 s[6:7], s[30:31], 8
	v_readlane_b32 s4, v254, 53
	v_exp_f32_e32 v0, v0
	v_readlane_b32 s5, v254, 54
	s_add_u32 s6, s4, s6
	s_addc_u32 s7, s5, s7
	v_ashrrev_i32_e32 v19, 31, v18
	v_lshl_add_u64 v[2:3], v[18:19], 2, s[6:7]
	global_store_dword v[2:3], v0, off
